# A/B of the GEMM-loop s_setprio edit: hipcc's mid-phase setprio 0/1 flip pairs restored (36 sites) on top of v18
# speedup vs baseline: 1.0094x; 1.0094x over previous
.LBB0_74:
	s_add_i32 s7, s6, 2
	s_add_u32 s8, s10, 0x80
	s_addc_u32 s9, s11, 0
	s_add_i32 s14, 0, 0x10000
	s_cmp_eq_u32 s94, s6
	s_cselect_b32 s13, s75, s9
	s_cselect_b32 s12, s74, s8
	s_cselect_b32 s9, s79, s5
	s_cselect_b32 s8, s78, s1
	s_add_i32 s6, 0, 0x14000
	v_add_u32_e32 v142, s14, v211
	v_add_u32_e32 v170, s6, v211
	ds_read_b128 v[130:133], v142
	ds_read_b128 v[134:137], v142 offset:1024
	ds_read_b128 v[138:141], v142 offset:2048
	ds_read_b128 v[142:145], v142 offset:3072
	ds_read_b128 v[158:161], v170
	ds_read_b128 v[162:165], v170 offset:1024
	ds_read_b128 v[166:169], v170 offset:2048
	ds_read_b128 v[170:173], v170 offset:3072
	v_lshl_add_u64 v[208:209], s[10:11], 0, v[154:155]
	s_add_i32 m0, s27, 0xc000
	ds_read_b128 v[174:177], v230
	ds_read_b128 v[178:181], v230 offset:1024
	ds_read_b128 v[182:185], v230 offset:2048
	ds_read_b128 v[186:189], v230 offset:3072
	ds_read_b128 v[190:193], v230 offset:4096
	ds_read_b128 v[194:197], v230 offset:5120
	ds_read_b128 v[198:201], v230 offset:6144
	ds_read_b128 v[204:207], v230 offset:7168
	global_load_lds_dwordx4 v[208:209], off
	v_lshl_add_u64 v[208:209], s[10:11], 0, v[156:157]
	s_add_i32 m0, s27, 0xe000
	s_nop 0
	global_load_lds_dwordx4 v[208:209], off
	s_waitcnt vmcnt(8)
	s_waitcnt lgkmcnt(0)
	s_barrier
	s_setprio 1
	v_mfma_f32_16x16x32_bf16 v[126:129], v[130:133], v[174:177], v[126:129]
	v_mfma_f32_16x16x32_bf16 v[122:125], v[138:141], v[174:177], v[122:125]
	v_mfma_f32_16x16x32_bf16 v[110:113], v[130:133], v[182:185], v[110:113]
	v_mfma_f32_16x16x32_bf16 v[106:109], v[138:141], v[182:185], v[106:109]
	v_mfma_f32_16x16x32_bf16 v[94:97], v[130:133], v[190:193], v[94:97]
	v_mfma_f32_16x16x32_bf16 v[90:93], v[138:141], v[190:193], v[90:93]
	v_mfma_f32_16x16x32_bf16 v[78:81], v[130:133], v[198:201], v[78:81]
	v_mfma_f32_16x16x32_bf16 v[74:77], v[138:141], v[198:201], v[74:77]
	v_mfma_f32_16x16x32_bf16 v[126:129], v[134:137], v[178:181], v[126:129]
	v_mfma_f32_16x16x32_bf16 v[122:125], v[142:145], v[178:181], v[122:125]
	v_mfma_f32_16x16x32_bf16 v[110:113], v[134:137], v[186:189], v[110:113]
	v_mfma_f32_16x16x32_bf16 v[106:109], v[142:145], v[186:189], v[106:109]
	v_mfma_f32_16x16x32_bf16 v[94:97], v[134:137], v[194:197], v[94:97]
	v_mfma_f32_16x16x32_bf16 v[90:93], v[142:145], v[194:197], v[90:93]
	v_mfma_f32_16x16x32_bf16 v[78:81], v[134:137], v[204:207], v[78:81]
	v_mfma_f32_16x16x32_bf16 v[74:77], v[142:145], v[204:207], v[74:77]
	s_setprio 0
	s_setprio 1
	v_mfma_f32_16x16x32_bf16 v[118:121], v[158:161], v[174:177], v[118:121]
	v_mfma_f32_16x16x32_bf16 v[114:117], v[166:169], v[174:177], v[114:117]
	v_mfma_f32_16x16x32_bf16 v[102:105], v[158:161], v[182:185], v[102:105]
	v_mfma_f32_16x16x32_bf16 v[98:101], v[166:169], v[182:185], v[98:101]
	v_mfma_f32_16x16x32_bf16 v[86:89], v[158:161], v[190:193], v[86:89]
	v_mfma_f32_16x16x32_bf16 v[82:85], v[166:169], v[190:193], v[82:85]
	v_mfma_f32_16x16x32_bf16 v[70:73], v[158:161], v[198:201], v[70:73]
	v_mfma_f32_16x16x32_bf16 v[66:69], v[166:169], v[198:201], v[66:69]
	v_mfma_f32_16x16x32_bf16 v[118:121], v[162:165], v[178:181], v[118:121]
	v_mfma_f32_16x16x32_bf16 v[114:117], v[170:173], v[178:181], v[114:117]
	v_mfma_f32_16x16x32_bf16 v[102:105], v[162:165], v[186:189], v[102:105]
	v_mfma_f32_16x16x32_bf16 v[98:101], v[170:173], v[186:189], v[98:101]
	v_mfma_f32_16x16x32_bf16 v[86:89], v[162:165], v[194:197], v[86:89]
	v_mfma_f32_16x16x32_bf16 v[82:85], v[170:173], v[194:197], v[82:85]
	v_mfma_f32_16x16x32_bf16 v[70:73], v[162:165], v[204:207], v[70:73]
	v_mfma_f32_16x16x32_bf16 v[66:69], v[170:173], v[204:207], v[66:69]
	s_setprio 0
	s_barrier
	s_add_i32 s14, s14, s26
	v_lshl_add_u64 v[208:209], s[8:9], 0, v[146:147]
	s_mov_b32 m0, s14
	ds_read_b128 v[174:177], v230 offset:16384
	ds_read_b128 v[178:181], v230 offset:17408
	ds_read_b128 v[182:185], v230 offset:18432
	ds_read_b128 v[186:189], v230 offset:19456
	ds_read_b128 v[190:193], v230 offset:20480
	ds_read_b128 v[194:197], v230 offset:21504
	ds_read_b128 v[198:201], v230 offset:22528
	ds_read_b128 v[204:207], v230 offset:23552
	global_load_lds_dwordx4 v[208:209], off
	s_add_i32 m0, s14, 0x2000
	v_lshl_add_u64 v[212:213], s[8:9], 0, v[150:151]
	s_add_u32 s8, s8, s60
	s_addc_u32 s9, s9, s61
	s_add_i32 s6, s6, s26
	global_load_lds_dwordx4 v[212:213], off
	v_lshl_add_u64 v[214:215], s[8:9], 0, v[146:147]
	s_mov_b32 m0, s6
	v_lshl_add_u64 v[216:217], s[8:9], 0, v[150:151]
	global_load_lds_dwordx4 v[214:215], off
	s_add_i32 m0, s6, 0x2000
	v_lshl_add_u64 v[218:219], s[12:13], 0, v[148:149]
	global_load_lds_dwordx4 v[216:217], off
	s_mov_b32 m0, s27
	v_lshl_add_u64 v[220:221], s[12:13], 0, v[152:153]
	global_load_lds_dwordx4 v[218:219], off
	s_mov_b32 m0, s38
	s_nop 0
	global_load_lds_dwordx4 v[220:221], off
	s_waitcnt vmcnt(8)
	s_waitcnt lgkmcnt(0)
	s_barrier
	s_setprio 1
	v_mfma_f32_16x16x32_bf16 v[62:65], v[130:133], v[174:177], v[62:65]
	v_mfma_f32_16x16x32_bf16 v[58:61], v[138:141], v[174:177], v[58:61]
	v_mfma_f32_16x16x32_bf16 v[46:49], v[130:133], v[182:185], v[46:49]
	v_mfma_f32_16x16x32_bf16 v[42:45], v[138:141], v[182:185], v[42:45]
	v_mfma_f32_16x16x32_bf16 v[30:33], v[130:133], v[190:193], v[30:33]
	v_mfma_f32_16x16x32_bf16 v[26:29], v[138:141], v[190:193], v[26:29]
	v_mfma_f32_16x16x32_bf16 v[14:17], v[130:133], v[198:201], v[14:17]
	v_mfma_f32_16x16x32_bf16 v[10:13], v[138:141], v[198:201], v[10:13]
	v_mfma_f32_16x16x32_bf16 v[62:65], v[134:137], v[178:181], v[62:65]
	v_mfma_f32_16x16x32_bf16 v[58:61], v[142:145], v[178:181], v[58:61]
	v_mfma_f32_16x16x32_bf16 v[46:49], v[134:137], v[186:189], v[46:49]
	v_mfma_f32_16x16x32_bf16 v[42:45], v[142:145], v[186:189], v[42:45]
	v_mfma_f32_16x16x32_bf16 v[30:33], v[134:137], v[194:197], v[30:33]
	v_mfma_f32_16x16x32_bf16 v[26:29], v[142:145], v[194:197], v[26:29]
	v_mfma_f32_16x16x32_bf16 v[14:17], v[134:137], v[204:207], v[14:17]
	v_mfma_f32_16x16x32_bf16 v[10:13], v[142:145], v[204:207], v[10:13]
	s_setprio 0
	s_setprio 1
	v_mfma_f32_16x16x32_bf16 v[54:57], v[158:161], v[174:177], v[54:57]
	v_mfma_f32_16x16x32_bf16 v[50:53], v[166:169], v[174:177], v[50:53]
	v_mfma_f32_16x16x32_bf16 v[38:41], v[158:161], v[182:185], v[38:41]
	v_mfma_f32_16x16x32_bf16 v[34:37], v[166:169], v[182:185], v[34:37]
	v_mfma_f32_16x16x32_bf16 v[22:25], v[158:161], v[190:193], v[22:25]
	v_mfma_f32_16x16x32_bf16 v[18:21], v[166:169], v[190:193], v[18:21]
	v_mfma_f32_16x16x32_bf16 v[6:9], v[158:161], v[198:201], v[6:9]
	v_mfma_f32_16x16x32_bf16 v[2:5], v[166:169], v[198:201], v[2:5]
	v_mfma_f32_16x16x32_bf16 v[54:57], v[162:165], v[178:181], v[54:57]
	v_mfma_f32_16x16x32_bf16 v[50:53], v[170:173], v[178:181], v[50:53]
	v_mfma_f32_16x16x32_bf16 v[38:41], v[162:165], v[186:189], v[38:41]
	v_mfma_f32_16x16x32_bf16 v[34:37], v[170:173], v[186:189], v[34:37]
	v_mfma_f32_16x16x32_bf16 v[22:25], v[162:165], v[194:197], v[22:25]
	v_mfma_f32_16x16x32_bf16 v[18:21], v[170:173], v[194:197], v[18:21]
	v_mfma_f32_16x16x32_bf16 v[6:9], v[162:165], v[204:207], v[6:9]
	v_mfma_f32_16x16x32_bf16 v[2:5], v[170:173], v[204:207], v[2:5]
	s_setprio 0
	s_barrier
	s_add_i32 s6, 0, 0x18000
	s_add_i32 s14, 0, 0x1c000
	v_add_u32_e32 v142, s6, v211
	v_add_u32_e32 v170, s14, v211
	ds_read_b128 v[130:133], v142
	ds_read_b128 v[134:137], v142 offset:1024
	ds_read_b128 v[138:141], v142 offset:2048
	ds_read_b128 v[142:145], v142 offset:3072
	ds_read_b128 v[158:161], v170
	ds_read_b128 v[162:165], v170 offset:1024
	ds_read_b128 v[166:169], v170 offset:2048
	ds_read_b128 v[170:173], v170 offset:3072
	s_add_u32 s8, s12, s60
	s_addc_u32 s9, s13, s61
	s_mov_b32 m0, s39
	v_lshl_add_u64 v[222:223], s[8:9], 0, v[148:149]
	ds_read_b128 v[174:177], v230 offset:32768
	ds_read_b128 v[178:181], v230 offset:33792
	ds_read_b128 v[182:185], v230 offset:34816
	ds_read_b128 v[186:189], v230 offset:35840
	ds_read_b128 v[190:193], v230 offset:36864
	ds_read_b128 v[194:197], v230 offset:37888
	ds_read_b128 v[198:201], v230 offset:38912
	ds_read_b128 v[204:207], v230 offset:39936
	global_load_lds_dwordx4 v[222:223], off
	v_lshl_add_u64 v[222:223], s[8:9], 0, v[152:153]
	s_mov_b32 m0, s87
	s_nop 0
	global_load_lds_dwordx4 v[222:223], off
	s_waitcnt vmcnt(8)
	s_waitcnt lgkmcnt(0)
	s_barrier
	s_setprio 1
	v_mfma_f32_16x16x32_bf16 v[126:129], v[130:133], v[174:177], v[126:129]
	v_mfma_f32_16x16x32_bf16 v[122:125], v[138:141], v[174:177], v[122:125]
	v_mfma_f32_16x16x32_bf16 v[110:113], v[130:133], v[182:185], v[110:113]
	v_mfma_f32_16x16x32_bf16 v[106:109], v[138:141], v[182:185], v[106:109]
	v_mfma_f32_16x16x32_bf16 v[94:97], v[130:133], v[190:193], v[94:97]
	v_mfma_f32_16x16x32_bf16 v[90:93], v[138:141], v[190:193], v[90:93]
	v_mfma_f32_16x16x32_bf16 v[78:81], v[130:133], v[198:201], v[78:81]
	v_mfma_f32_16x16x32_bf16 v[74:77], v[138:141], v[198:201], v[74:77]
	v_mfma_f32_16x16x32_bf16 v[126:129], v[134:137], v[178:181], v[126:129]
	v_mfma_f32_16x16x32_bf16 v[122:125], v[142:145], v[178:181], v[122:125]
	v_mfma_f32_16x16x32_bf16 v[110:113], v[134:137], v[186:189], v[110:113]
	v_mfma_f32_16x16x32_bf16 v[106:109], v[142:145], v[186:189], v[106:109]
	v_mfma_f32_16x16x32_bf16 v[94:97], v[134:137], v[194:197], v[94:97]
	v_mfma_f32_16x16x32_bf16 v[90:93], v[142:145], v[194:197], v[90:93]
	v_mfma_f32_16x16x32_bf16 v[78:81], v[134:137], v[204:207], v[78:81]
	v_mfma_f32_16x16x32_bf16 v[74:77], v[142:145], v[204:207], v[74:77]
	s_setprio 0
	s_setprio 1
	v_mfma_f32_16x16x32_bf16 v[118:121], v[158:161], v[174:177], v[118:121]
	v_mfma_f32_16x16x32_bf16 v[114:117], v[166:169], v[174:177], v[114:117]
	v_mfma_f32_16x16x32_bf16 v[102:105], v[158:161], v[182:185], v[102:105]
	v_mfma_f32_16x16x32_bf16 v[98:101], v[166:169], v[182:185], v[98:101]
	v_mfma_f32_16x16x32_bf16 v[86:89], v[158:161], v[190:193], v[86:89]
	v_mfma_f32_16x16x32_bf16 v[82:85], v[166:169], v[190:193], v[82:85]
	v_mfma_f32_16x16x32_bf16 v[70:73], v[158:161], v[198:201], v[70:73]
	v_mfma_f32_16x16x32_bf16 v[66:69], v[166:169], v[198:201], v[66:69]
	v_mfma_f32_16x16x32_bf16 v[118:121], v[162:165], v[178:181], v[118:121]
	v_mfma_f32_16x16x32_bf16 v[114:117], v[170:173], v[178:181], v[114:117]
	v_mfma_f32_16x16x32_bf16 v[102:105], v[162:165], v[186:189], v[102:105]
	v_mfma_f32_16x16x32_bf16 v[98:101], v[170:173], v[186:189], v[98:101]
	v_mfma_f32_16x16x32_bf16 v[86:89], v[162:165], v[194:197], v[86:89]
	v_mfma_f32_16x16x32_bf16 v[82:85], v[170:173], v[194:197], v[82:85]
	v_mfma_f32_16x16x32_bf16 v[70:73], v[162:165], v[204:207], v[70:73]
	v_mfma_f32_16x16x32_bf16 v[66:69], v[170:173], v[204:207], v[66:69]
	s_setprio 0
	s_barrier
	s_add_i32 s6, s6, s26
	v_lshl_add_u64 v[208:209], v[208:209], 0, s[28:29]
	s_mov_b32 m0, s6
	ds_read_b128 v[174:177], v230 offset:49152
	ds_read_b128 v[178:181], v230 offset:50176
	ds_read_b128 v[182:185], v230 offset:51200
	ds_read_b128 v[186:189], v230 offset:52224
	ds_read_b128 v[190:193], v230 offset:53248
	ds_read_b128 v[194:197], v230 offset:54272
	ds_read_b128 v[198:201], v230 offset:55296
	ds_read_b128 v[204:207], v230 offset:56320
	global_load_lds_dwordx4 v[208:209], off
	v_lshl_add_u64 v[208:209], v[212:213], 0, s[28:29]
	s_add_i32 m0, s6, 0x2000
	s_add_i32 s6, s14, s26
	global_load_lds_dwordx4 v[208:209], off
	v_lshl_add_u64 v[208:209], v[214:215], 0, s[28:29]
	s_mov_b32 m0, s6
	s_nop 0
	global_load_lds_dwordx4 v[208:209], off
	v_lshl_add_u64 v[208:209], v[216:217], 0, s[28:29]
	s_add_i32 m0, s6, 0x2000
	s_nop 0
	global_load_lds_dwordx4 v[208:209], off
	v_lshl_add_u64 v[208:209], v[218:219], 0, s[28:29]
	s_mov_b32 m0, s88
	s_nop 0
	global_load_lds_dwordx4 v[208:209], off
	v_lshl_add_u64 v[208:209], v[220:221], 0, s[28:29]
	s_mov_b32 m0, s89
	s_nop 0
	global_load_lds_dwordx4 v[208:209], off
	s_waitcnt vmcnt(8)
	s_waitcnt lgkmcnt(0)
	s_barrier
	s_setprio 1
	v_mfma_f32_16x16x32_bf16 v[62:65], v[130:133], v[174:177], v[62:65]
	v_mfma_f32_16x16x32_bf16 v[58:61], v[138:141], v[174:177], v[58:61]
	v_mfma_f32_16x16x32_bf16 v[46:49], v[130:133], v[182:185], v[46:49]
	v_mfma_f32_16x16x32_bf16 v[42:45], v[138:141], v[182:185], v[42:45]
	v_mfma_f32_16x16x32_bf16 v[30:33], v[130:133], v[190:193], v[30:33]
	v_mfma_f32_16x16x32_bf16 v[26:29], v[138:141], v[190:193], v[26:29]
	v_mfma_f32_16x16x32_bf16 v[14:17], v[130:133], v[198:201], v[14:17]
	v_mfma_f32_16x16x32_bf16 v[10:13], v[138:141], v[198:201], v[10:13]
	v_mfma_f32_16x16x32_bf16 v[62:65], v[134:137], v[178:181], v[62:65]
	v_mfma_f32_16x16x32_bf16 v[58:61], v[142:145], v[178:181], v[58:61]
	v_mfma_f32_16x16x32_bf16 v[46:49], v[134:137], v[186:189], v[46:49]
	v_mfma_f32_16x16x32_bf16 v[42:45], v[142:145], v[186:189], v[42:45]
	v_mfma_f32_16x16x32_bf16 v[30:33], v[134:137], v[194:197], v[30:33]
	v_mfma_f32_16x16x32_bf16 v[26:29], v[142:145], v[194:197], v[26:29]
	v_mfma_f32_16x16x32_bf16 v[14:17], v[134:137], v[204:207], v[14:17]
	v_mfma_f32_16x16x32_bf16 v[10:13], v[142:145], v[204:207], v[10:13]
	s_setprio 0
	s_setprio 1
	v_mfma_f32_16x16x32_bf16 v[54:57], v[158:161], v[174:177], v[54:57]
	v_mfma_f32_16x16x32_bf16 v[50:53], v[166:169], v[174:177], v[50:53]
	v_mfma_f32_16x16x32_bf16 v[38:41], v[158:161], v[182:185], v[38:41]
	v_mfma_f32_16x16x32_bf16 v[34:37], v[166:169], v[182:185], v[34:37]
	v_mfma_f32_16x16x32_bf16 v[22:25], v[158:161], v[190:193], v[22:25]
	v_mfma_f32_16x16x32_bf16 v[18:21], v[166:169], v[190:193], v[18:21]
	v_mfma_f32_16x16x32_bf16 v[6:9], v[158:161], v[198:201], v[6:9]
	v_mfma_f32_16x16x32_bf16 v[2:5], v[166:169], v[198:201], v[2:5]
	v_mfma_f32_16x16x32_bf16 v[54:57], v[162:165], v[178:181], v[54:57]
	v_mfma_f32_16x16x32_bf16 v[50:53], v[170:173], v[178:181], v[50:53]
	v_mfma_f32_16x16x32_bf16 v[38:41], v[162:165], v[186:189], v[38:41]
	v_mfma_f32_16x16x32_bf16 v[34:37], v[170:173], v[186:189], v[34:37]
	v_mfma_f32_16x16x32_bf16 v[22:25], v[162:165], v[194:197], v[22:25]
	v_mfma_f32_16x16x32_bf16 v[18:21], v[170:173], v[194:197], v[18:21]
	v_mfma_f32_16x16x32_bf16 v[6:9], v[162:165], v[204:207], v[6:9]
	v_mfma_f32_16x16x32_bf16 v[2:5], v[170:173], v[204:207], v[2:5]
	s_setprio 0
	s_barrier
	s_add_u32 s1, s1, 0x100
	s_addc_u32 s5, s5, 0
	s_add_u32 s10, s10, 0x100
	s_addc_u32 s11, s11, 0
	s_cmp_ge_i32 s7, s91
	s_mov_b32 s6, s7
	s_cbranch_scc0 .LBB0_74

.LBB0_237:
	s_add_i32 s7, s6, 2
	s_add_u32 s8, s0, 0x80
	s_addc_u32 s9, s1, 0
	s_add_i32 s12, 0, 0x10000
	s_cmp_eq_u32 s74, s6
	s_cselect_b32 s11, s65, s9
	s_cselect_b32 s10, s64, s8
	s_cselect_b32 s9, s67, s5
	s_cselect_b32 s8, s66, s4
	s_add_i32 s6, 0, 0x14000
	v_add_u32_e32 v154, s12, v183
	v_add_u32_e32 v170, s6, v183
	ds_read_b128 v[130:133], v154
	ds_read_b128 v[134:137], v154 offset:1024
	ds_read_b128 v[150:153], v154 offset:2048
	ds_read_b128 v[154:157], v154 offset:3072
	ds_read_b128 v[158:161], v170
	ds_read_b128 v[162:165], v170 offset:1024
	ds_read_b128 v[166:169], v170 offset:2048
	ds_read_b128 v[170:173], v170 offset:3072
	v_lshl_add_u64 v[210:211], s[0:1], 0, v[146:147]
	s_add_i32 m0, s39, 0xc000
	ds_read_b128 v[174:177], v184
	ds_read_b128 v[178:181], v184 offset:1024
	ds_read_b128 v[186:189], v184 offset:2048
	ds_read_b128 v[190:193], v184 offset:3072
	ds_read_b128 v[194:197], v184 offset:4096
	ds_read_b128 v[198:201], v184 offset:5120
	ds_read_b128 v[202:205], v184 offset:6144
	ds_read_b128 v[206:209], v184 offset:7168
	global_load_lds_dwordx4 v[210:211], off
	v_lshl_add_u64 v[210:211], s[0:1], 0, v[148:149]
	s_add_i32 m0, s39, 0xe000
	s_nop 0
	global_load_lds_dwordx4 v[210:211], off
	s_waitcnt vmcnt(8)
	s_waitcnt lgkmcnt(0)
	s_barrier
	s_setprio 1
	v_mfma_f32_16x16x32_bf16 v[126:129], v[130:133], v[174:177], v[126:129]
	v_mfma_f32_16x16x32_bf16 v[122:125], v[150:153], v[174:177], v[122:125]
	v_mfma_f32_16x16x32_bf16 v[110:113], v[130:133], v[186:189], v[110:113]
	v_mfma_f32_16x16x32_bf16 v[106:109], v[150:153], v[186:189], v[106:109]
	v_mfma_f32_16x16x32_bf16 v[94:97], v[130:133], v[194:197], v[94:97]
	v_mfma_f32_16x16x32_bf16 v[90:93], v[150:153], v[194:197], v[90:93]
	v_mfma_f32_16x16x32_bf16 v[78:81], v[130:133], v[202:205], v[78:81]
	v_mfma_f32_16x16x32_bf16 v[74:77], v[150:153], v[202:205], v[74:77]
	v_mfma_f32_16x16x32_bf16 v[126:129], v[134:137], v[178:181], v[126:129]
	v_mfma_f32_16x16x32_bf16 v[122:125], v[154:157], v[178:181], v[122:125]
	v_mfma_f32_16x16x32_bf16 v[110:113], v[134:137], v[190:193], v[110:113]
	v_mfma_f32_16x16x32_bf16 v[106:109], v[154:157], v[190:193], v[106:109]
	v_mfma_f32_16x16x32_bf16 v[94:97], v[134:137], v[198:201], v[94:97]
	v_mfma_f32_16x16x32_bf16 v[90:93], v[154:157], v[198:201], v[90:93]
	v_mfma_f32_16x16x32_bf16 v[78:81], v[134:137], v[206:209], v[78:81]
	v_mfma_f32_16x16x32_bf16 v[74:77], v[154:157], v[206:209], v[74:77]
	s_setprio 0
	s_setprio 1
	v_mfma_f32_16x16x32_bf16 v[118:121], v[158:161], v[174:177], v[118:121]
	v_mfma_f32_16x16x32_bf16 v[114:117], v[166:169], v[174:177], v[114:117]
	v_mfma_f32_16x16x32_bf16 v[102:105], v[158:161], v[186:189], v[102:105]
	v_mfma_f32_16x16x32_bf16 v[98:101], v[166:169], v[186:189], v[98:101]
	v_mfma_f32_16x16x32_bf16 v[86:89], v[158:161], v[194:197], v[86:89]
	v_mfma_f32_16x16x32_bf16 v[82:85], v[166:169], v[194:197], v[82:85]
	v_mfma_f32_16x16x32_bf16 v[70:73], v[158:161], v[202:205], v[70:73]
	v_mfma_f32_16x16x32_bf16 v[66:69], v[166:169], v[202:205], v[66:69]
	v_mfma_f32_16x16x32_bf16 v[118:121], v[162:165], v[178:181], v[118:121]
	v_mfma_f32_16x16x32_bf16 v[114:117], v[170:173], v[178:181], v[114:117]
	v_mfma_f32_16x16x32_bf16 v[102:105], v[162:165], v[190:193], v[102:105]
	v_mfma_f32_16x16x32_bf16 v[98:101], v[170:173], v[190:193], v[98:101]
	v_mfma_f32_16x16x32_bf16 v[86:89], v[162:165], v[198:201], v[86:89]
	v_mfma_f32_16x16x32_bf16 v[82:85], v[170:173], v[198:201], v[82:85]
	v_mfma_f32_16x16x32_bf16 v[70:73], v[162:165], v[206:209], v[70:73]
	v_mfma_f32_16x16x32_bf16 v[66:69], v[170:173], v[206:209], v[66:69]
	s_setprio 0
	s_barrier
	s_add_i32 s12, s12, s38
	v_lshl_add_u64 v[210:211], s[8:9], 0, v[144:145]
	s_mov_b32 m0, s12
	ds_read_b128 v[174:177], v184 offset:16384
	ds_read_b128 v[178:181], v184 offset:17408
	ds_read_b128 v[186:189], v184 offset:18432
	ds_read_b128 v[190:193], v184 offset:19456
	ds_read_b128 v[194:197], v184 offset:20480
	ds_read_b128 v[198:201], v184 offset:21504
	ds_read_b128 v[202:205], v184 offset:22528
	ds_read_b128 v[206:209], v184 offset:23552
	global_load_lds_dwordx4 v[210:211], off
	s_add_i32 m0, s12, 0x2000
	v_lshl_add_u64 v[212:213], s[8:9], 0, v[140:141]
	s_add_u32 s8, s8, s46
	s_addc_u32 s9, s9, s47
	s_add_i32 s6, s6, s38
	global_load_lds_dwordx4 v[212:213], off
	v_lshl_add_u64 v[214:215], s[8:9], 0, v[144:145]
	s_mov_b32 m0, s6
	v_lshl_add_u64 v[216:217], s[8:9], 0, v[140:141]
	global_load_lds_dwordx4 v[214:215], off
	s_add_i32 m0, s6, 0x2000
	v_lshl_add_u64 v[218:219], s[10:11], 0, v[142:143]
	global_load_lds_dwordx4 v[216:217], off
	s_mov_b32 m0, s39
	v_lshl_add_u64 v[220:221], s[10:11], 0, v[138:139]
	global_load_lds_dwordx4 v[218:219], off
	s_mov_b32 m0, s70
	s_nop 0
	global_load_lds_dwordx4 v[220:221], off
	s_waitcnt vmcnt(8)
	s_waitcnt lgkmcnt(0)
	s_barrier
	s_setprio 1
	v_mfma_f32_16x16x32_bf16 v[62:65], v[130:133], v[174:177], v[62:65]
	v_mfma_f32_16x16x32_bf16 v[58:61], v[150:153], v[174:177], v[58:61]
	v_mfma_f32_16x16x32_bf16 v[46:49], v[130:133], v[186:189], v[46:49]
	v_mfma_f32_16x16x32_bf16 v[42:45], v[150:153], v[186:189], v[42:45]
	v_mfma_f32_16x16x32_bf16 v[30:33], v[130:133], v[194:197], v[30:33]
	v_mfma_f32_16x16x32_bf16 v[26:29], v[150:153], v[194:197], v[26:29]
	v_mfma_f32_16x16x32_bf16 v[14:17], v[130:133], v[202:205], v[14:17]
	v_mfma_f32_16x16x32_bf16 v[10:13], v[150:153], v[202:205], v[10:13]
	v_mfma_f32_16x16x32_bf16 v[62:65], v[134:137], v[178:181], v[62:65]
	v_mfma_f32_16x16x32_bf16 v[58:61], v[154:157], v[178:181], v[58:61]
	v_mfma_f32_16x16x32_bf16 v[46:49], v[134:137], v[190:193], v[46:49]
	v_mfma_f32_16x16x32_bf16 v[42:45], v[154:157], v[190:193], v[42:45]
	v_mfma_f32_16x16x32_bf16 v[30:33], v[134:137], v[198:201], v[30:33]
	v_mfma_f32_16x16x32_bf16 v[26:29], v[154:157], v[198:201], v[26:29]
	v_mfma_f32_16x16x32_bf16 v[14:17], v[134:137], v[206:209], v[14:17]
	v_mfma_f32_16x16x32_bf16 v[10:13], v[154:157], v[206:209], v[10:13]
	s_setprio 0
	s_setprio 1
	v_mfma_f32_16x16x32_bf16 v[54:57], v[158:161], v[174:177], v[54:57]
	v_mfma_f32_16x16x32_bf16 v[50:53], v[166:169], v[174:177], v[50:53]
	v_mfma_f32_16x16x32_bf16 v[38:41], v[158:161], v[186:189], v[38:41]
	v_mfma_f32_16x16x32_bf16 v[34:37], v[166:169], v[186:189], v[34:37]
	v_mfma_f32_16x16x32_bf16 v[22:25], v[158:161], v[194:197], v[22:25]
	v_mfma_f32_16x16x32_bf16 v[18:21], v[166:169], v[194:197], v[18:21]
	v_mfma_f32_16x16x32_bf16 v[6:9], v[158:161], v[202:205], v[6:9]
	v_mfma_f32_16x16x32_bf16 v[2:5], v[166:169], v[202:205], v[2:5]
	v_mfma_f32_16x16x32_bf16 v[54:57], v[162:165], v[178:181], v[54:57]
	v_mfma_f32_16x16x32_bf16 v[50:53], v[170:173], v[178:181], v[50:53]
	v_mfma_f32_16x16x32_bf16 v[38:41], v[162:165], v[190:193], v[38:41]
	v_mfma_f32_16x16x32_bf16 v[34:37], v[170:173], v[190:193], v[34:37]
	v_mfma_f32_16x16x32_bf16 v[22:25], v[162:165], v[198:201], v[22:25]
	v_mfma_f32_16x16x32_bf16 v[18:21], v[170:173], v[198:201], v[18:21]
	v_mfma_f32_16x16x32_bf16 v[6:9], v[162:165], v[206:209], v[6:9]
	v_mfma_f32_16x16x32_bf16 v[2:5], v[170:173], v[206:209], v[2:5]
	s_setprio 0
	s_barrier
	s_add_i32 s6, 0, 0x18000
	s_add_i32 s12, 0, 0x1c000
	v_add_u32_e32 v154, s6, v183
	v_add_u32_e32 v170, s12, v183
	ds_read_b128 v[130:133], v154
	ds_read_b128 v[134:137], v154 offset:1024
	ds_read_b128 v[150:153], v154 offset:2048
	ds_read_b128 v[154:157], v154 offset:3072
	ds_read_b128 v[158:161], v170
	ds_read_b128 v[162:165], v170 offset:1024
	ds_read_b128 v[166:169], v170 offset:2048
	ds_read_b128 v[170:173], v170 offset:3072
	s_add_u32 s8, s10, s46
	s_addc_u32 s9, s11, s47
	s_mov_b32 m0, s71
	v_lshl_add_u64 v[222:223], s[8:9], 0, v[142:143]
	ds_read_b128 v[174:177], v184 offset:32768
	ds_read_b128 v[178:181], v184 offset:33792
	ds_read_b128 v[186:189], v184 offset:34816
	ds_read_b128 v[190:193], v184 offset:35840
	ds_read_b128 v[194:197], v184 offset:36864
	ds_read_b128 v[198:201], v184 offset:37888
	ds_read_b128 v[202:205], v184 offset:38912
	ds_read_b128 v[206:209], v184 offset:39936
	global_load_lds_dwordx4 v[222:223], off
	v_lshl_add_u64 v[222:223], s[8:9], 0, v[138:139]
	s_mov_b32 m0, s72
	s_nop 0
	global_load_lds_dwordx4 v[222:223], off
	s_waitcnt vmcnt(8)
	s_waitcnt lgkmcnt(0)
	s_barrier
	s_setprio 1
	v_mfma_f32_16x16x32_bf16 v[126:129], v[130:133], v[174:177], v[126:129]
	v_mfma_f32_16x16x32_bf16 v[122:125], v[150:153], v[174:177], v[122:125]
	v_mfma_f32_16x16x32_bf16 v[110:113], v[130:133], v[186:189], v[110:113]
	v_mfma_f32_16x16x32_bf16 v[106:109], v[150:153], v[186:189], v[106:109]
	v_mfma_f32_16x16x32_bf16 v[94:97], v[130:133], v[194:197], v[94:97]
	v_mfma_f32_16x16x32_bf16 v[90:93], v[150:153], v[194:197], v[90:93]
	v_mfma_f32_16x16x32_bf16 v[78:81], v[130:133], v[202:205], v[78:81]
	v_mfma_f32_16x16x32_bf16 v[74:77], v[150:153], v[202:205], v[74:77]
	v_mfma_f32_16x16x32_bf16 v[126:129], v[134:137], v[178:181], v[126:129]
	v_mfma_f32_16x16x32_bf16 v[122:125], v[154:157], v[178:181], v[122:125]
	v_mfma_f32_16x16x32_bf16 v[110:113], v[134:137], v[190:193], v[110:113]
	v_mfma_f32_16x16x32_bf16 v[106:109], v[154:157], v[190:193], v[106:109]
	v_mfma_f32_16x16x32_bf16 v[94:97], v[134:137], v[198:201], v[94:97]
	v_mfma_f32_16x16x32_bf16 v[90:93], v[154:157], v[198:201], v[90:93]
	v_mfma_f32_16x16x32_bf16 v[78:81], v[134:137], v[206:209], v[78:81]
	v_mfma_f32_16x16x32_bf16 v[74:77], v[154:157], v[206:209], v[74:77]
	s_setprio 0
	s_setprio 1
	v_mfma_f32_16x16x32_bf16 v[118:121], v[158:161], v[174:177], v[118:121]
	v_mfma_f32_16x16x32_bf16 v[114:117], v[166:169], v[174:177], v[114:117]
	v_mfma_f32_16x16x32_bf16 v[102:105], v[158:161], v[186:189], v[102:105]
	v_mfma_f32_16x16x32_bf16 v[98:101], v[166:169], v[186:189], v[98:101]
	v_mfma_f32_16x16x32_bf16 v[86:89], v[158:161], v[194:197], v[86:89]
	v_mfma_f32_16x16x32_bf16 v[82:85], v[166:169], v[194:197], v[82:85]
	v_mfma_f32_16x16x32_bf16 v[70:73], v[158:161], v[202:205], v[70:73]
	v_mfma_f32_16x16x32_bf16 v[66:69], v[166:169], v[202:205], v[66:69]
	v_mfma_f32_16x16x32_bf16 v[118:121], v[162:165], v[178:181], v[118:121]
	v_mfma_f32_16x16x32_bf16 v[114:117], v[170:173], v[178:181], v[114:117]
	v_mfma_f32_16x16x32_bf16 v[102:105], v[162:165], v[190:193], v[102:105]
	v_mfma_f32_16x16x32_bf16 v[98:101], v[170:173], v[190:193], v[98:101]
	v_mfma_f32_16x16x32_bf16 v[86:89], v[162:165], v[198:201], v[86:89]
	v_mfma_f32_16x16x32_bf16 v[82:85], v[170:173], v[198:201], v[82:85]
	v_mfma_f32_16x16x32_bf16 v[70:73], v[162:165], v[206:209], v[70:73]
	v_mfma_f32_16x16x32_bf16 v[66:69], v[170:173], v[206:209], v[66:69]
	s_setprio 0
	s_barrier
	s_add_i32 s6, s6, s38
	v_lshl_add_u64 v[210:211], v[210:211], 0, s[28:29]
	s_mov_b32 m0, s6
	ds_read_b128 v[174:177], v184 offset:49152
	ds_read_b128 v[178:181], v184 offset:50176
	ds_read_b128 v[186:189], v184 offset:51200
	ds_read_b128 v[190:193], v184 offset:52224
	ds_read_b128 v[194:197], v184 offset:53248
	ds_read_b128 v[198:201], v184 offset:54272
	ds_read_b128 v[202:205], v184 offset:55296
	ds_read_b128 v[206:209], v184 offset:56320
	global_load_lds_dwordx4 v[210:211], off
	v_lshl_add_u64 v[210:211], v[212:213], 0, s[28:29]
	s_add_i32 m0, s6, 0x2000
	s_add_i32 s6, s12, s38
	global_load_lds_dwordx4 v[210:211], off
	v_lshl_add_u64 v[210:211], v[214:215], 0, s[28:29]
	s_mov_b32 m0, s6
	s_nop 0
	global_load_lds_dwordx4 v[210:211], off
	v_lshl_add_u64 v[210:211], v[216:217], 0, s[28:29]
	s_add_i32 m0, s6, 0x2000
	s_nop 0
	global_load_lds_dwordx4 v[210:211], off
	v_lshl_add_u64 v[210:211], v[218:219], 0, s[28:29]
	s_mov_b32 m0, s24
	s_nop 0
	global_load_lds_dwordx4 v[210:211], off
	v_lshl_add_u64 v[210:211], v[220:221], 0, s[28:29]
	s_mov_b32 m0, s25
	s_nop 0
	global_load_lds_dwordx4 v[210:211], off
	s_waitcnt vmcnt(8)
	s_waitcnt lgkmcnt(0)
	s_barrier
	s_setprio 1
	v_mfma_f32_16x16x32_bf16 v[62:65], v[130:133], v[174:177], v[62:65]
	v_mfma_f32_16x16x32_bf16 v[58:61], v[150:153], v[174:177], v[58:61]
	v_mfma_f32_16x16x32_bf16 v[46:49], v[130:133], v[186:189], v[46:49]
	v_mfma_f32_16x16x32_bf16 v[42:45], v[150:153], v[186:189], v[42:45]
	v_mfma_f32_16x16x32_bf16 v[30:33], v[130:133], v[194:197], v[30:33]
	v_mfma_f32_16x16x32_bf16 v[26:29], v[150:153], v[194:197], v[26:29]
	v_mfma_f32_16x16x32_bf16 v[14:17], v[130:133], v[202:205], v[14:17]
	v_mfma_f32_16x16x32_bf16 v[10:13], v[150:153], v[202:205], v[10:13]
	v_mfma_f32_16x16x32_bf16 v[62:65], v[134:137], v[178:181], v[62:65]
	v_mfma_f32_16x16x32_bf16 v[58:61], v[154:157], v[178:181], v[58:61]
	v_mfma_f32_16x16x32_bf16 v[46:49], v[134:137], v[190:193], v[46:49]
	v_mfma_f32_16x16x32_bf16 v[42:45], v[154:157], v[190:193], v[42:45]
	v_mfma_f32_16x16x32_bf16 v[30:33], v[134:137], v[198:201], v[30:33]
	v_mfma_f32_16x16x32_bf16 v[26:29], v[154:157], v[198:201], v[26:29]
	v_mfma_f32_16x16x32_bf16 v[14:17], v[134:137], v[206:209], v[14:17]
	v_mfma_f32_16x16x32_bf16 v[10:13], v[154:157], v[206:209], v[10:13]
	s_setprio 0
	s_setprio 1
	v_mfma_f32_16x16x32_bf16 v[54:57], v[158:161], v[174:177], v[54:57]
	v_mfma_f32_16x16x32_bf16 v[50:53], v[166:169], v[174:177], v[50:53]
	v_mfma_f32_16x16x32_bf16 v[38:41], v[158:161], v[186:189], v[38:41]
	v_mfma_f32_16x16x32_bf16 v[34:37], v[166:169], v[186:189], v[34:37]
	v_mfma_f32_16x16x32_bf16 v[22:25], v[158:161], v[194:197], v[22:25]
	v_mfma_f32_16x16x32_bf16 v[18:21], v[166:169], v[194:197], v[18:21]
	v_mfma_f32_16x16x32_bf16 v[6:9], v[158:161], v[202:205], v[6:9]
	v_mfma_f32_16x16x32_bf16 v[2:5], v[166:169], v[202:205], v[2:5]
	v_mfma_f32_16x16x32_bf16 v[54:57], v[162:165], v[178:181], v[54:57]
	v_mfma_f32_16x16x32_bf16 v[50:53], v[170:173], v[178:181], v[50:53]
	v_mfma_f32_16x16x32_bf16 v[38:41], v[162:165], v[190:193], v[38:41]
	v_mfma_f32_16x16x32_bf16 v[34:37], v[170:173], v[190:193], v[34:37]
	v_mfma_f32_16x16x32_bf16 v[22:25], v[162:165], v[198:201], v[22:25]
	v_mfma_f32_16x16x32_bf16 v[18:21], v[170:173], v[198:201], v[18:21]
	v_mfma_f32_16x16x32_bf16 v[6:9], v[162:165], v[206:209], v[6:9]
	v_mfma_f32_16x16x32_bf16 v[2:5], v[170:173], v[206:209], v[2:5]
	s_setprio 0
	s_barrier
	s_add_u32 s4, s4, 0x100
	s_addc_u32 s5, s5, 0
	s_add_u32 s0, s0, 0x100
	s_addc_u32 s1, s1, 0
	s_cmp_ge_i32 s7, s26
	s_mov_b32 s6, s7
	s_cbranch_scc0 .LBB0_237

.LBB0_299:
	s_add_i32 s8, s7, 2
	s_add_u32 s9, s0, 0x80
	s_addc_u32 s10, s1, 0
	s_add_i32 s14, 0, 0x10000
	s_cmp_eq_u32 s69, s7
	s_cselect_b32 s11, s61, s10
	s_cselect_b32 s10, s60, s9
	s_cselect_b32 s13, s63, s6
	s_cselect_b32 s12, s62, s5
	s_add_i32 s7, 0, 0x14000
	v_add_u32_e32 v154, s14, v181
	v_add_u32_e32 v170, s7, v181
	ds_read_b128 v[142:145], v154
	ds_read_b128 v[146:149], v154 offset:1024
	ds_read_b128 v[150:153], v154 offset:2048
	ds_read_b128 v[154:157], v154 offset:3072
	ds_read_b128 v[158:161], v170
	ds_read_b128 v[162:165], v170 offset:1024
	ds_read_b128 v[166:169], v170 offset:2048
	ds_read_b128 v[170:173], v170 offset:3072
	v_lshl_add_u64 v[178:179], s[0:1], 0, v[138:139]
	s_add_i32 m0, s25, 0xc000
	ds_read_b128 v[174:177], v182
	ds_read_b128 v[184:187], v182 offset:1024
	ds_read_b128 v[188:191], v182 offset:2048
	ds_read_b128 v[192:195], v182 offset:3072
	ds_read_b128 v[196:199], v182 offset:4096
	ds_read_b128 v[200:203], v182 offset:5120
	ds_read_b128 v[204:207], v182 offset:6144
	ds_read_b128 v[212:215], v182 offset:7168
	global_load_lds_dwordx4 v[178:179], off
	v_lshl_add_u64 v[178:179], s[0:1], 0, v[140:141]
	s_add_i32 m0, s25, 0xe000
	s_nop 0
	global_load_lds_dwordx4 v[178:179], off
	s_waitcnt vmcnt(8)
	s_waitcnt lgkmcnt(0)
	s_barrier
	s_setprio 1
	v_mfma_f32_16x16x32_bf16 v[126:129], v[142:145], v[174:177], v[126:129]
	v_mfma_f32_16x16x32_bf16 v[122:125], v[150:153], v[174:177], v[122:125]
	v_mfma_f32_16x16x32_bf16 v[118:121], v[142:145], v[188:191], v[118:121]
	v_mfma_f32_16x16x32_bf16 v[114:117], v[150:153], v[188:191], v[114:117]
	v_mfma_f32_16x16x32_bf16 v[110:113], v[142:145], v[196:199], v[110:113]
	v_mfma_f32_16x16x32_bf16 v[106:109], v[150:153], v[196:199], v[106:109]
	v_mfma_f32_16x16x32_bf16 v[102:105], v[142:145], v[204:207], v[102:105]
	v_mfma_f32_16x16x32_bf16 v[98:101], v[150:153], v[204:207], v[98:101]
	v_mfma_f32_16x16x32_bf16 v[126:129], v[146:149], v[184:187], v[126:129]
	v_mfma_f32_16x16x32_bf16 v[122:125], v[154:157], v[184:187], v[122:125]
	v_mfma_f32_16x16x32_bf16 v[118:121], v[146:149], v[192:195], v[118:121]
	v_mfma_f32_16x16x32_bf16 v[114:117], v[154:157], v[192:195], v[114:117]
	v_mfma_f32_16x16x32_bf16 v[110:113], v[146:149], v[200:203], v[110:113]
	v_mfma_f32_16x16x32_bf16 v[106:109], v[154:157], v[200:203], v[106:109]
	v_mfma_f32_16x16x32_bf16 v[102:105], v[146:149], v[212:215], v[102:105]
	v_mfma_f32_16x16x32_bf16 v[98:101], v[154:157], v[212:215], v[98:101]
	s_setprio 0
	s_setprio 1
	v_mfma_f32_16x16x32_bf16 v[6:9], v[158:161], v[174:177], v[6:9]
	v_mfma_f32_16x16x32_bf16 v[2:5], v[166:169], v[174:177], v[2:5]
	v_mfma_f32_16x16x32_bf16 v[14:17], v[158:161], v[188:191], v[14:17]
	v_mfma_f32_16x16x32_bf16 v[10:13], v[166:169], v[188:191], v[10:13]
	v_mfma_f32_16x16x32_bf16 v[22:25], v[158:161], v[196:199], v[22:25]
	v_mfma_f32_16x16x32_bf16 v[18:21], v[166:169], v[196:199], v[18:21]
	v_mfma_f32_16x16x32_bf16 v[34:37], v[158:161], v[204:207], v[34:37]
	v_mfma_f32_16x16x32_bf16 v[26:29], v[166:169], v[204:207], v[26:29]
	v_mfma_f32_16x16x32_bf16 v[6:9], v[162:165], v[184:187], v[6:9]
	v_mfma_f32_16x16x32_bf16 v[2:5], v[170:173], v[184:187], v[2:5]
	v_mfma_f32_16x16x32_bf16 v[14:17], v[162:165], v[192:195], v[14:17]
	v_mfma_f32_16x16x32_bf16 v[10:13], v[170:173], v[192:195], v[10:13]
	v_mfma_f32_16x16x32_bf16 v[22:25], v[162:165], v[200:203], v[22:25]
	v_mfma_f32_16x16x32_bf16 v[18:21], v[170:173], v[200:203], v[18:21]
	v_mfma_f32_16x16x32_bf16 v[34:37], v[162:165], v[212:215], v[34:37]
	v_mfma_f32_16x16x32_bf16 v[26:29], v[170:173], v[212:215], v[26:29]
	s_setprio 0
	s_barrier
	s_add_i32 s9, s14, s24
	v_lshl_add_u64 v[178:179], s[12:13], 0, v[136:137]
	s_mov_b32 m0, s9
	ds_read_b128 v[174:177], v182 offset:16384
	ds_read_b128 v[184:187], v182 offset:17408
	ds_read_b128 v[188:191], v182 offset:18432
	ds_read_b128 v[192:195], v182 offset:19456
	ds_read_b128 v[196:199], v182 offset:20480
	ds_read_b128 v[200:203], v182 offset:21504
	ds_read_b128 v[204:207], v182 offset:22528
	ds_read_b128 v[212:215], v182 offset:23552
	global_load_lds_dwordx4 v[178:179], off
	s_add_i32 m0, s9, 0x2000
	v_lshl_add_u64 v[208:209], s[12:13], 0, v[132:133]
	s_add_u32 s12, s12, s48
	s_addc_u32 s13, s13, s49
	s_add_i32 s7, s7, s24
	global_load_lds_dwordx4 v[208:209], off
	v_lshl_add_u64 v[210:211], s[12:13], 0, v[136:137]
	s_mov_b32 m0, s7
	v_lshl_add_u64 v[216:217], s[12:13], 0, v[132:133]
	global_load_lds_dwordx4 v[210:211], off
	s_add_i32 m0, s7, 0x2000
	v_lshl_add_u64 v[218:219], s[10:11], 0, v[134:135]
	global_load_lds_dwordx4 v[216:217], off
	s_mov_b32 m0, s25
	v_lshl_add_u64 v[220:221], s[10:11], 0, v[130:131]
	global_load_lds_dwordx4 v[218:219], off
	s_mov_b32 m0, s26
	s_nop 0
	global_load_lds_dwordx4 v[220:221], off
	s_waitcnt vmcnt(8)
	s_waitcnt lgkmcnt(0)
	s_barrier
	s_setprio 1
	v_mfma_f32_16x16x32_bf16 v[94:97], v[142:145], v[174:177], v[94:97]
	v_mfma_f32_16x16x32_bf16 v[90:93], v[150:153], v[174:177], v[90:93]
	v_mfma_f32_16x16x32_bf16 v[86:89], v[142:145], v[188:191], v[86:89]
	v_mfma_f32_16x16x32_bf16 v[82:85], v[150:153], v[188:191], v[82:85]
	v_mfma_f32_16x16x32_bf16 v[78:81], v[142:145], v[196:199], v[78:81]
	v_mfma_f32_16x16x32_bf16 v[74:77], v[150:153], v[196:199], v[74:77]
	v_mfma_f32_16x16x32_bf16 v[70:73], v[142:145], v[204:207], v[70:73]
	v_mfma_f32_16x16x32_bf16 v[66:69], v[150:153], v[204:207], v[66:69]
	v_mfma_f32_16x16x32_bf16 v[94:97], v[146:149], v[184:187], v[94:97]
	v_mfma_f32_16x16x32_bf16 v[90:93], v[154:157], v[184:187], v[90:93]
	v_mfma_f32_16x16x32_bf16 v[86:89], v[146:149], v[192:195], v[86:89]
	v_mfma_f32_16x16x32_bf16 v[82:85], v[154:157], v[192:195], v[82:85]
	v_mfma_f32_16x16x32_bf16 v[78:81], v[146:149], v[200:203], v[78:81]
	v_mfma_f32_16x16x32_bf16 v[74:77], v[154:157], v[200:203], v[74:77]
	v_mfma_f32_16x16x32_bf16 v[70:73], v[146:149], v[212:215], v[70:73]
	v_mfma_f32_16x16x32_bf16 v[66:69], v[154:157], v[212:215], v[66:69]
	s_setprio 0
	s_setprio 1
	v_mfma_f32_16x16x32_bf16 v[38:41], v[158:161], v[174:177], v[38:41]
	v_mfma_f32_16x16x32_bf16 v[30:33], v[166:169], v[174:177], v[30:33]
	v_mfma_f32_16x16x32_bf16 v[46:49], v[158:161], v[188:191], v[46:49]
	v_mfma_f32_16x16x32_bf16 v[42:45], v[166:169], v[188:191], v[42:45]
	v_mfma_f32_16x16x32_bf16 v[58:61], v[158:161], v[196:199], v[58:61]
	v_mfma_f32_16x16x32_bf16 v[50:53], v[166:169], v[196:199], v[50:53]
	v_mfma_f32_16x16x32_bf16 v[62:65], v[158:161], v[204:207], v[62:65]
	v_mfma_f32_16x16x32_bf16 v[54:57], v[166:169], v[204:207], v[54:57]
	v_mfma_f32_16x16x32_bf16 v[38:41], v[162:165], v[184:187], v[38:41]
	v_mfma_f32_16x16x32_bf16 v[30:33], v[170:173], v[184:187], v[30:33]
	v_mfma_f32_16x16x32_bf16 v[46:49], v[162:165], v[192:195], v[46:49]
	v_mfma_f32_16x16x32_bf16 v[42:45], v[170:173], v[192:195], v[42:45]
	v_mfma_f32_16x16x32_bf16 v[58:61], v[162:165], v[200:203], v[58:61]
	v_mfma_f32_16x16x32_bf16 v[50:53], v[170:173], v[200:203], v[50:53]
	v_mfma_f32_16x16x32_bf16 v[62:65], v[162:165], v[212:215], v[62:65]
	v_mfma_f32_16x16x32_bf16 v[54:57], v[170:173], v[212:215], v[54:57]
	s_setprio 0
	s_barrier
	s_add_i32 s7, 0, 0x18000
	s_add_i32 s9, 0, 0x1c000
	v_add_u32_e32 v154, s7, v181
	v_add_u32_e32 v170, s9, v181
	ds_read_b128 v[142:145], v154
	ds_read_b128 v[146:149], v154 offset:1024
	ds_read_b128 v[150:153], v154 offset:2048
	ds_read_b128 v[154:157], v154 offset:3072
	ds_read_b128 v[158:161], v170
	ds_read_b128 v[162:165], v170 offset:1024
	ds_read_b128 v[166:169], v170 offset:2048
	ds_read_b128 v[170:173], v170 offset:3072
	s_add_u32 s10, s10, s48
	s_addc_u32 s11, s11, s49
	s_mov_b32 m0, s27
	v_lshl_add_u64 v[222:223], s[10:11], 0, v[134:135]
	ds_read_b128 v[174:177], v182 offset:32768
	ds_read_b128 v[184:187], v182 offset:33792
	ds_read_b128 v[188:191], v182 offset:34816
	ds_read_b128 v[192:195], v182 offset:35840
	ds_read_b128 v[196:199], v182 offset:36864
	ds_read_b128 v[200:203], v182 offset:37888
	ds_read_b128 v[204:207], v182 offset:38912
	ds_read_b128 v[212:215], v182 offset:39936
	global_load_lds_dwordx4 v[222:223], off
	v_lshl_add_u64 v[222:223], s[10:11], 0, v[130:131]
	s_mov_b32 m0, s38
	s_nop 0
	global_load_lds_dwordx4 v[222:223], off
	s_waitcnt vmcnt(8)
	s_waitcnt lgkmcnt(0)
	s_barrier
	s_setprio 1
	v_mfma_f32_16x16x32_bf16 v[126:129], v[142:145], v[174:177], v[126:129]
	v_mfma_f32_16x16x32_bf16 v[122:125], v[150:153], v[174:177], v[122:125]
	v_mfma_f32_16x16x32_bf16 v[118:121], v[142:145], v[188:191], v[118:121]
	v_mfma_f32_16x16x32_bf16 v[114:117], v[150:153], v[188:191], v[114:117]
	v_mfma_f32_16x16x32_bf16 v[110:113], v[142:145], v[196:199], v[110:113]
	v_mfma_f32_16x16x32_bf16 v[106:109], v[150:153], v[196:199], v[106:109]
	v_mfma_f32_16x16x32_bf16 v[102:105], v[142:145], v[204:207], v[102:105]
	v_mfma_f32_16x16x32_bf16 v[98:101], v[150:153], v[204:207], v[98:101]
	v_mfma_f32_16x16x32_bf16 v[126:129], v[146:149], v[184:187], v[126:129]
	v_mfma_f32_16x16x32_bf16 v[122:125], v[154:157], v[184:187], v[122:125]
	v_mfma_f32_16x16x32_bf16 v[118:121], v[146:149], v[192:195], v[118:121]
	v_mfma_f32_16x16x32_bf16 v[114:117], v[154:157], v[192:195], v[114:117]
	v_mfma_f32_16x16x32_bf16 v[110:113], v[146:149], v[200:203], v[110:113]
	v_mfma_f32_16x16x32_bf16 v[106:109], v[154:157], v[200:203], v[106:109]
	v_mfma_f32_16x16x32_bf16 v[102:105], v[146:149], v[212:215], v[102:105]
	v_mfma_f32_16x16x32_bf16 v[98:101], v[154:157], v[212:215], v[98:101]
	s_setprio 0
	s_setprio 1
	v_mfma_f32_16x16x32_bf16 v[6:9], v[158:161], v[174:177], v[6:9]
	v_mfma_f32_16x16x32_bf16 v[2:5], v[166:169], v[174:177], v[2:5]
	v_mfma_f32_16x16x32_bf16 v[14:17], v[158:161], v[188:191], v[14:17]
	v_mfma_f32_16x16x32_bf16 v[10:13], v[166:169], v[188:191], v[10:13]
	v_mfma_f32_16x16x32_bf16 v[22:25], v[158:161], v[196:199], v[22:25]
	v_mfma_f32_16x16x32_bf16 v[18:21], v[166:169], v[196:199], v[18:21]
	v_mfma_f32_16x16x32_bf16 v[34:37], v[158:161], v[204:207], v[34:37]
	v_mfma_f32_16x16x32_bf16 v[26:29], v[166:169], v[204:207], v[26:29]
	v_mfma_f32_16x16x32_bf16 v[6:9], v[162:165], v[184:187], v[6:9]
	v_mfma_f32_16x16x32_bf16 v[2:5], v[170:173], v[184:187], v[2:5]
	v_mfma_f32_16x16x32_bf16 v[14:17], v[162:165], v[192:195], v[14:17]
	v_mfma_f32_16x16x32_bf16 v[10:13], v[170:173], v[192:195], v[10:13]
	v_mfma_f32_16x16x32_bf16 v[22:25], v[162:165], v[200:203], v[22:25]
	v_mfma_f32_16x16x32_bf16 v[18:21], v[170:173], v[200:203], v[18:21]
	v_mfma_f32_16x16x32_bf16 v[34:37], v[162:165], v[212:215], v[34:37]
	v_mfma_f32_16x16x32_bf16 v[26:29], v[170:173], v[212:215], v[26:29]
	s_setprio 0
	s_barrier
	s_add_i32 s7, s7, s24
	v_lshl_add_u64 v[178:179], v[178:179], 0, s[28:29]
	s_mov_b32 m0, s7
	ds_read_b128 v[174:177], v182 offset:49152
	ds_read_b128 v[184:187], v182 offset:50176
	ds_read_b128 v[188:191], v182 offset:51200
	ds_read_b128 v[192:195], v182 offset:52224
	ds_read_b128 v[196:199], v182 offset:53248
	ds_read_b128 v[200:203], v182 offset:54272
	ds_read_b128 v[204:207], v182 offset:55296
	ds_read_b128 v[212:215], v182 offset:56320
	global_load_lds_dwordx4 v[178:179], off
	v_lshl_add_u64 v[178:179], v[208:209], 0, s[28:29]
	s_add_i32 m0, s7, 0x2000
	s_add_i32 s7, s9, s24
	global_load_lds_dwordx4 v[178:179], off
	v_lshl_add_u64 v[178:179], v[210:211], 0, s[28:29]
	s_mov_b32 m0, s7
	s_nop 0
	global_load_lds_dwordx4 v[178:179], off
	v_lshl_add_u64 v[178:179], v[216:217], 0, s[28:29]
	s_add_i32 m0, s7, 0x2000
	s_nop 0
	global_load_lds_dwordx4 v[178:179], off
	v_lshl_add_u64 v[178:179], v[218:219], 0, s[28:29]
	s_mov_b32 m0, s39
	s_nop 0
	global_load_lds_dwordx4 v[178:179], off
	v_lshl_add_u64 v[178:179], v[220:221], 0, s[28:29]
	s_mov_b32 m0, s66
	s_nop 0
	global_load_lds_dwordx4 v[178:179], off
	s_waitcnt vmcnt(8)
	s_waitcnt lgkmcnt(0)
	s_barrier
	s_setprio 1
	v_mfma_f32_16x16x32_bf16 v[94:97], v[142:145], v[174:177], v[94:97]
	v_mfma_f32_16x16x32_bf16 v[90:93], v[150:153], v[174:177], v[90:93]
	v_mfma_f32_16x16x32_bf16 v[86:89], v[142:145], v[188:191], v[86:89]
	v_mfma_f32_16x16x32_bf16 v[82:85], v[150:153], v[188:191], v[82:85]
	v_mfma_f32_16x16x32_bf16 v[78:81], v[142:145], v[196:199], v[78:81]
	v_mfma_f32_16x16x32_bf16 v[74:77], v[150:153], v[196:199], v[74:77]
	v_mfma_f32_16x16x32_bf16 v[70:73], v[142:145], v[204:207], v[70:73]
	v_mfma_f32_16x16x32_bf16 v[66:69], v[150:153], v[204:207], v[66:69]
	v_mfma_f32_16x16x32_bf16 v[94:97], v[146:149], v[184:187], v[94:97]
	v_mfma_f32_16x16x32_bf16 v[90:93], v[154:157], v[184:187], v[90:93]
	v_mfma_f32_16x16x32_bf16 v[86:89], v[146:149], v[192:195], v[86:89]
	v_mfma_f32_16x16x32_bf16 v[82:85], v[154:157], v[192:195], v[82:85]
	v_mfma_f32_16x16x32_bf16 v[78:81], v[146:149], v[200:203], v[78:81]
	v_mfma_f32_16x16x32_bf16 v[74:77], v[154:157], v[200:203], v[74:77]
	v_mfma_f32_16x16x32_bf16 v[70:73], v[146:149], v[212:215], v[70:73]
	v_mfma_f32_16x16x32_bf16 v[66:69], v[154:157], v[212:215], v[66:69]
	s_setprio 0
	s_setprio 1
	v_mfma_f32_16x16x32_bf16 v[38:41], v[158:161], v[174:177], v[38:41]
	v_mfma_f32_16x16x32_bf16 v[30:33], v[166:169], v[174:177], v[30:33]
	v_mfma_f32_16x16x32_bf16 v[46:49], v[158:161], v[188:191], v[46:49]
	v_mfma_f32_16x16x32_bf16 v[42:45], v[166:169], v[188:191], v[42:45]
	v_mfma_f32_16x16x32_bf16 v[58:61], v[158:161], v[196:199], v[58:61]
	v_mfma_f32_16x16x32_bf16 v[50:53], v[166:169], v[196:199], v[50:53]
	v_mfma_f32_16x16x32_bf16 v[62:65], v[158:161], v[204:207], v[62:65]
	v_mfma_f32_16x16x32_bf16 v[54:57], v[166:169], v[204:207], v[54:57]
	v_mfma_f32_16x16x32_bf16 v[38:41], v[162:165], v[184:187], v[38:41]
	v_mfma_f32_16x16x32_bf16 v[30:33], v[170:173], v[184:187], v[30:33]
	v_mfma_f32_16x16x32_bf16 v[46:49], v[162:165], v[192:195], v[46:49]
	v_mfma_f32_16x16x32_bf16 v[42:45], v[170:173], v[192:195], v[42:45]
	v_mfma_f32_16x16x32_bf16 v[58:61], v[162:165], v[200:203], v[58:61]
	v_mfma_f32_16x16x32_bf16 v[50:53], v[170:173], v[200:203], v[50:53]
	v_mfma_f32_16x16x32_bf16 v[62:65], v[162:165], v[212:215], v[62:65]
	v_mfma_f32_16x16x32_bf16 v[54:57], v[170:173], v[212:215], v[54:57]
	s_setprio 0
	s_barrier
	s_add_u32 s5, s5, 0x100
	s_addc_u32 s6, s6, 0
	s_add_u32 s0, s0, 0x100
	s_addc_u32 s1, s1, 0
	s_cmp_ge_i32 s8, s67
	s_mov_b32 s7, s8
	s_cbranch_scc0 .LBB0_299

.LBB0_522:
	s_add_i32 s7, s6, 2
	s_add_u32 s8, s10, 0x80
	s_addc_u32 s9, s11, 0
	s_add_i32 s14, 0, 0x10000
	s_cmp_eq_u32 s75, s6
	s_cselect_b32 s13, s61, s9
	s_cselect_b32 s12, s60, s8
	s_cselect_b32 s9, s63, s5
	s_cselect_b32 s8, s62, s1
	s_add_i32 s6, 0, 0x14000
	v_add_u32_e32 v154, s14, v182
	v_add_u32_e32 v170, s6, v182
	ds_read_b128 v[142:145], v154
	ds_read_b128 v[146:149], v154 offset:1024
	ds_read_b128 v[150:153], v154 offset:2048
	ds_read_b128 v[154:157], v154 offset:3072
	ds_read_b128 v[158:161], v170
	ds_read_b128 v[162:165], v170 offset:1024
	ds_read_b128 v[166:169], v170 offset:2048
	ds_read_b128 v[172:175], v170 offset:3072
	v_lshl_add_u64 v[180:181], s[10:11], 0, v[138:139]
	s_add_i32 m0, s67, 0xc000
	ds_read_b128 v[176:179], v183
	ds_read_b128 v[184:187], v183 offset:1024
	ds_read_b128 v[188:191], v183 offset:2048
	ds_read_b128 v[192:195], v183 offset:3072
	ds_read_b128 v[196:199], v183 offset:4096
	ds_read_b128 v[200:203], v183 offset:5120
	ds_read_b128 v[204:207], v183 offset:6144
	ds_read_b128 v[212:215], v183 offset:7168
	global_load_lds_dwordx4 v[180:181], off
	v_lshl_add_u64 v[180:181], s[10:11], 0, v[140:141]
	s_add_i32 m0, s67, 0xe000
	s_nop 0
	global_load_lds_dwordx4 v[180:181], off
	s_waitcnt vmcnt(8)
	s_waitcnt lgkmcnt(0)
	s_barrier
	s_setprio 1
	v_mfma_f32_16x16x32_bf16 v[126:129], v[142:145], v[176:179], v[126:129]
	v_mfma_f32_16x16x32_bf16 v[122:125], v[150:153], v[176:179], v[122:125]
	v_mfma_f32_16x16x32_bf16 v[110:113], v[142:145], v[188:191], v[110:113]
	v_mfma_f32_16x16x32_bf16 v[106:109], v[150:153], v[188:191], v[106:109]
	v_mfma_f32_16x16x32_bf16 v[94:97], v[142:145], v[196:199], v[94:97]
	v_mfma_f32_16x16x32_bf16 v[90:93], v[150:153], v[196:199], v[90:93]
	v_mfma_f32_16x16x32_bf16 v[78:81], v[142:145], v[204:207], v[78:81]
	v_mfma_f32_16x16x32_bf16 v[74:77], v[150:153], v[204:207], v[74:77]
	v_mfma_f32_16x16x32_bf16 v[126:129], v[146:149], v[184:187], v[126:129]
	v_mfma_f32_16x16x32_bf16 v[122:125], v[154:157], v[184:187], v[122:125]
	v_mfma_f32_16x16x32_bf16 v[110:113], v[146:149], v[192:195], v[110:113]
	v_mfma_f32_16x16x32_bf16 v[106:109], v[154:157], v[192:195], v[106:109]
	v_mfma_f32_16x16x32_bf16 v[94:97], v[146:149], v[200:203], v[94:97]
	v_mfma_f32_16x16x32_bf16 v[90:93], v[154:157], v[200:203], v[90:93]
	v_mfma_f32_16x16x32_bf16 v[78:81], v[146:149], v[212:215], v[78:81]
	v_mfma_f32_16x16x32_bf16 v[74:77], v[154:157], v[212:215], v[74:77]
	s_setprio 0
	s_setprio 1
	v_mfma_f32_16x16x32_bf16 v[118:121], v[158:161], v[176:179], v[118:121]
	v_mfma_f32_16x16x32_bf16 v[114:117], v[166:169], v[176:179], v[114:117]
	v_mfma_f32_16x16x32_bf16 v[102:105], v[158:161], v[188:191], v[102:105]
	v_mfma_f32_16x16x32_bf16 v[98:101], v[166:169], v[188:191], v[98:101]
	v_mfma_f32_16x16x32_bf16 v[86:89], v[158:161], v[196:199], v[86:89]
	v_mfma_f32_16x16x32_bf16 v[82:85], v[166:169], v[196:199], v[82:85]
	v_mfma_f32_16x16x32_bf16 v[70:73], v[158:161], v[204:207], v[70:73]
	v_mfma_f32_16x16x32_bf16 v[66:69], v[166:169], v[204:207], v[66:69]
	v_mfma_f32_16x16x32_bf16 v[118:121], v[162:165], v[184:187], v[118:121]
	v_mfma_f32_16x16x32_bf16 v[114:117], v[172:175], v[184:187], v[114:117]
	v_mfma_f32_16x16x32_bf16 v[102:105], v[162:165], v[192:195], v[102:105]
	v_mfma_f32_16x16x32_bf16 v[98:101], v[172:175], v[192:195], v[98:101]
	v_mfma_f32_16x16x32_bf16 v[86:89], v[162:165], v[200:203], v[86:89]
	v_mfma_f32_16x16x32_bf16 v[82:85], v[172:175], v[200:203], v[82:85]
	v_mfma_f32_16x16x32_bf16 v[70:73], v[162:165], v[212:215], v[70:73]
	v_mfma_f32_16x16x32_bf16 v[66:69], v[172:175], v[212:215], v[66:69]
	s_setprio 0
	s_barrier
	s_add_i32 s14, s14, s66
	v_lshl_add_u64 v[180:181], s[8:9], 0, v[136:137]
	s_mov_b32 m0, s14
	ds_read_b128 v[176:179], v183 offset:16384
	ds_read_b128 v[184:187], v183 offset:17408
	ds_read_b128 v[188:191], v183 offset:18432
	ds_read_b128 v[192:195], v183 offset:19456
	ds_read_b128 v[196:199], v183 offset:20480
	ds_read_b128 v[200:203], v183 offset:21504
	ds_read_b128 v[204:207], v183 offset:22528
	ds_read_b128 v[212:215], v183 offset:23552
	global_load_lds_dwordx4 v[180:181], off
	s_add_i32 m0, s14, 0x2000
	v_lshl_add_u64 v[208:209], s[8:9], 0, v[132:133]
	s_add_u32 s8, s8, s50
	s_addc_u32 s9, s9, s51
	s_add_i32 s6, s6, s66
	global_load_lds_dwordx4 v[208:209], off
	v_lshl_add_u64 v[216:217], s[8:9], 0, v[136:137]
	s_mov_b32 m0, s6
	v_lshl_add_u64 v[218:219], s[8:9], 0, v[132:133]
	global_load_lds_dwordx4 v[216:217], off
	s_add_i32 m0, s6, 0x2000
	v_lshl_add_u64 v[220:221], s[12:13], 0, v[134:135]
	global_load_lds_dwordx4 v[218:219], off
	s_mov_b32 m0, s67
	v_lshl_add_u64 v[222:223], s[12:13], 0, v[130:131]
	global_load_lds_dwordx4 v[220:221], off
	s_mov_b32 m0, s68
	s_nop 0
	global_load_lds_dwordx4 v[222:223], off
	s_waitcnt vmcnt(8)
	s_waitcnt lgkmcnt(0)
	s_barrier
	s_setprio 1
	v_mfma_f32_16x16x32_bf16 v[62:65], v[142:145], v[176:179], v[62:65]
	v_mfma_f32_16x16x32_bf16 v[58:61], v[150:153], v[176:179], v[58:61]
	v_mfma_f32_16x16x32_bf16 v[46:49], v[142:145], v[188:191], v[46:49]
	v_mfma_f32_16x16x32_bf16 v[42:45], v[150:153], v[188:191], v[42:45]
	v_mfma_f32_16x16x32_bf16 v[30:33], v[142:145], v[196:199], v[30:33]
	v_mfma_f32_16x16x32_bf16 v[26:29], v[150:153], v[196:199], v[26:29]
	v_mfma_f32_16x16x32_bf16 v[14:17], v[142:145], v[204:207], v[14:17]
	v_mfma_f32_16x16x32_bf16 v[10:13], v[150:153], v[204:207], v[10:13]
	v_mfma_f32_16x16x32_bf16 v[62:65], v[146:149], v[184:187], v[62:65]
	v_mfma_f32_16x16x32_bf16 v[58:61], v[154:157], v[184:187], v[58:61]
	v_mfma_f32_16x16x32_bf16 v[46:49], v[146:149], v[192:195], v[46:49]
	v_mfma_f32_16x16x32_bf16 v[42:45], v[154:157], v[192:195], v[42:45]
	v_mfma_f32_16x16x32_bf16 v[30:33], v[146:149], v[200:203], v[30:33]
	v_mfma_f32_16x16x32_bf16 v[26:29], v[154:157], v[200:203], v[26:29]
	v_mfma_f32_16x16x32_bf16 v[14:17], v[146:149], v[212:215], v[14:17]
	v_mfma_f32_16x16x32_bf16 v[10:13], v[154:157], v[212:215], v[10:13]
	s_setprio 0
	s_setprio 1
	v_mfma_f32_16x16x32_bf16 v[54:57], v[158:161], v[176:179], v[54:57]
	v_mfma_f32_16x16x32_bf16 v[50:53], v[166:169], v[176:179], v[50:53]
	v_mfma_f32_16x16x32_bf16 v[38:41], v[158:161], v[188:191], v[38:41]
	v_mfma_f32_16x16x32_bf16 v[34:37], v[166:169], v[188:191], v[34:37]
	v_mfma_f32_16x16x32_bf16 v[22:25], v[158:161], v[196:199], v[22:25]
	v_mfma_f32_16x16x32_bf16 v[18:21], v[166:169], v[196:199], v[18:21]
	v_mfma_f32_16x16x32_bf16 v[6:9], v[158:161], v[204:207], v[6:9]
	v_mfma_f32_16x16x32_bf16 v[2:5], v[166:169], v[204:207], v[2:5]
	v_mfma_f32_16x16x32_bf16 v[54:57], v[162:165], v[184:187], v[54:57]
	v_mfma_f32_16x16x32_bf16 v[50:53], v[172:175], v[184:187], v[50:53]
	v_mfma_f32_16x16x32_bf16 v[38:41], v[162:165], v[192:195], v[38:41]
	v_mfma_f32_16x16x32_bf16 v[34:37], v[172:175], v[192:195], v[34:37]
	v_mfma_f32_16x16x32_bf16 v[22:25], v[162:165], v[200:203], v[22:25]
	v_mfma_f32_16x16x32_bf16 v[18:21], v[172:175], v[200:203], v[18:21]
	v_mfma_f32_16x16x32_bf16 v[6:9], v[162:165], v[212:215], v[6:9]
	v_mfma_f32_16x16x32_bf16 v[2:5], v[172:175], v[212:215], v[2:5]
	s_setprio 0
	s_barrier
	s_add_i32 s6, 0, 0x18000
	s_add_i32 s14, 0, 0x1c000
	v_add_u32_e32 v154, s6, v182
	v_add_u32_e32 v170, s14, v182
	ds_read_b128 v[142:145], v154
	ds_read_b128 v[146:149], v154 offset:1024
	ds_read_b128 v[150:153], v154 offset:2048
	ds_read_b128 v[154:157], v154 offset:3072
	ds_read_b128 v[158:161], v170
	ds_read_b128 v[162:165], v170 offset:1024
	ds_read_b128 v[166:169], v170 offset:2048
	ds_read_b128 v[172:175], v170 offset:3072
	s_add_u32 s8, s12, s50
	s_addc_u32 s9, s13, s51
	s_mov_b32 m0, s69
	v_lshl_add_u64 v[224:225], s[8:9], 0, v[134:135]
	ds_read_b128 v[176:179], v183 offset:32768
	ds_read_b128 v[184:187], v183 offset:33792
	ds_read_b128 v[188:191], v183 offset:34816
	ds_read_b128 v[192:195], v183 offset:35840
	ds_read_b128 v[196:199], v183 offset:36864
	ds_read_b128 v[200:203], v183 offset:37888
	ds_read_b128 v[204:207], v183 offset:38912
	ds_read_b128 v[212:215], v183 offset:39936
	global_load_lds_dwordx4 v[224:225], off
	v_lshl_add_u64 v[224:225], s[8:9], 0, v[130:131]
	s_mov_b32 m0, s70
	s_nop 0
	global_load_lds_dwordx4 v[224:225], off
	s_waitcnt vmcnt(8)
	s_waitcnt lgkmcnt(0)
	s_barrier
	s_setprio 1
	v_mfma_f32_16x16x32_bf16 v[126:129], v[142:145], v[176:179], v[126:129]
	v_mfma_f32_16x16x32_bf16 v[122:125], v[150:153], v[176:179], v[122:125]
	v_mfma_f32_16x16x32_bf16 v[110:113], v[142:145], v[188:191], v[110:113]
	v_mfma_f32_16x16x32_bf16 v[106:109], v[150:153], v[188:191], v[106:109]
	v_mfma_f32_16x16x32_bf16 v[94:97], v[142:145], v[196:199], v[94:97]
	v_mfma_f32_16x16x32_bf16 v[90:93], v[150:153], v[196:199], v[90:93]
	v_mfma_f32_16x16x32_bf16 v[78:81], v[142:145], v[204:207], v[78:81]
	v_mfma_f32_16x16x32_bf16 v[74:77], v[150:153], v[204:207], v[74:77]
	v_mfma_f32_16x16x32_bf16 v[126:129], v[146:149], v[184:187], v[126:129]
	v_mfma_f32_16x16x32_bf16 v[122:125], v[154:157], v[184:187], v[122:125]
	v_mfma_f32_16x16x32_bf16 v[110:113], v[146:149], v[192:195], v[110:113]
	v_mfma_f32_16x16x32_bf16 v[106:109], v[154:157], v[192:195], v[106:109]
	v_mfma_f32_16x16x32_bf16 v[94:97], v[146:149], v[200:203], v[94:97]
	v_mfma_f32_16x16x32_bf16 v[90:93], v[154:157], v[200:203], v[90:93]
	v_mfma_f32_16x16x32_bf16 v[78:81], v[146:149], v[212:215], v[78:81]
	v_mfma_f32_16x16x32_bf16 v[74:77], v[154:157], v[212:215], v[74:77]
	s_setprio 0
	s_setprio 1
	v_mfma_f32_16x16x32_bf16 v[118:121], v[158:161], v[176:179], v[118:121]
	v_mfma_f32_16x16x32_bf16 v[114:117], v[166:169], v[176:179], v[114:117]
	v_mfma_f32_16x16x32_bf16 v[102:105], v[158:161], v[188:191], v[102:105]
	v_mfma_f32_16x16x32_bf16 v[98:101], v[166:169], v[188:191], v[98:101]
	v_mfma_f32_16x16x32_bf16 v[86:89], v[158:161], v[196:199], v[86:89]
	v_mfma_f32_16x16x32_bf16 v[82:85], v[166:169], v[196:199], v[82:85]
	v_mfma_f32_16x16x32_bf16 v[70:73], v[158:161], v[204:207], v[70:73]
	v_mfma_f32_16x16x32_bf16 v[66:69], v[166:169], v[204:207], v[66:69]
	v_mfma_f32_16x16x32_bf16 v[118:121], v[162:165], v[184:187], v[118:121]
	v_mfma_f32_16x16x32_bf16 v[114:117], v[172:175], v[184:187], v[114:117]
	v_mfma_f32_16x16x32_bf16 v[102:105], v[162:165], v[192:195], v[102:105]
	v_mfma_f32_16x16x32_bf16 v[98:101], v[172:175], v[192:195], v[98:101]
	v_mfma_f32_16x16x32_bf16 v[86:89], v[162:165], v[200:203], v[86:89]
	v_mfma_f32_16x16x32_bf16 v[82:85], v[172:175], v[200:203], v[82:85]
	v_mfma_f32_16x16x32_bf16 v[70:73], v[162:165], v[212:215], v[70:73]
	v_mfma_f32_16x16x32_bf16 v[66:69], v[172:175], v[212:215], v[66:69]
	s_setprio 0
	s_barrier
	s_add_i32 s6, s6, s66
	v_lshl_add_u64 v[180:181], v[180:181], 0, s[28:29]
	s_mov_b32 m0, s6
	ds_read_b128 v[176:179], v183 offset:49152
	ds_read_b128 v[184:187], v183 offset:50176
	ds_read_b128 v[188:191], v183 offset:51200
	ds_read_b128 v[192:195], v183 offset:52224
	ds_read_b128 v[196:199], v183 offset:53248
	ds_read_b128 v[200:203], v183 offset:54272
	ds_read_b128 v[204:207], v183 offset:55296
	ds_read_b128 v[212:215], v183 offset:56320
	global_load_lds_dwordx4 v[180:181], off
	v_lshl_add_u64 v[180:181], v[208:209], 0, s[28:29]
	s_add_i32 m0, s6, 0x2000
	s_add_i32 s6, s14, s66
	global_load_lds_dwordx4 v[180:181], off
	v_lshl_add_u64 v[180:181], v[216:217], 0, s[28:29]
	s_mov_b32 m0, s6
	s_nop 0
	global_load_lds_dwordx4 v[180:181], off
	v_lshl_add_u64 v[180:181], v[218:219], 0, s[28:29]
	s_add_i32 m0, s6, 0x2000
	s_nop 0
	global_load_lds_dwordx4 v[180:181], off
	v_lshl_add_u64 v[180:181], v[220:221], 0, s[28:29]
	s_mov_b32 m0, s71
	s_nop 0
	global_load_lds_dwordx4 v[180:181], off
	v_lshl_add_u64 v[180:181], v[222:223], 0, s[28:29]
	s_mov_b32 m0, s72
	s_nop 0
	global_load_lds_dwordx4 v[180:181], off
	s_waitcnt vmcnt(8)
	s_waitcnt lgkmcnt(0)
	s_barrier
	s_setprio 1
	v_mfma_f32_16x16x32_bf16 v[62:65], v[142:145], v[176:179], v[62:65]
	v_mfma_f32_16x16x32_bf16 v[58:61], v[150:153], v[176:179], v[58:61]
	v_mfma_f32_16x16x32_bf16 v[46:49], v[142:145], v[188:191], v[46:49]
	v_mfma_f32_16x16x32_bf16 v[42:45], v[150:153], v[188:191], v[42:45]
	v_mfma_f32_16x16x32_bf16 v[30:33], v[142:145], v[196:199], v[30:33]
	v_mfma_f32_16x16x32_bf16 v[26:29], v[150:153], v[196:199], v[26:29]
	v_mfma_f32_16x16x32_bf16 v[14:17], v[142:145], v[204:207], v[14:17]
	v_mfma_f32_16x16x32_bf16 v[10:13], v[150:153], v[204:207], v[10:13]
	v_mfma_f32_16x16x32_bf16 v[62:65], v[146:149], v[184:187], v[62:65]
	v_mfma_f32_16x16x32_bf16 v[58:61], v[154:157], v[184:187], v[58:61]
	v_mfma_f32_16x16x32_bf16 v[46:49], v[146:149], v[192:195], v[46:49]
	v_mfma_f32_16x16x32_bf16 v[42:45], v[154:157], v[192:195], v[42:45]
	v_mfma_f32_16x16x32_bf16 v[30:33], v[146:149], v[200:203], v[30:33]
	v_mfma_f32_16x16x32_bf16 v[26:29], v[154:157], v[200:203], v[26:29]
	v_mfma_f32_16x16x32_bf16 v[14:17], v[146:149], v[212:215], v[14:17]
	v_mfma_f32_16x16x32_bf16 v[10:13], v[154:157], v[212:215], v[10:13]
	s_setprio 0
	s_setprio 1
	v_mfma_f32_16x16x32_bf16 v[54:57], v[158:161], v[176:179], v[54:57]
	v_mfma_f32_16x16x32_bf16 v[50:53], v[166:169], v[176:179], v[50:53]
	v_mfma_f32_16x16x32_bf16 v[38:41], v[158:161], v[188:191], v[38:41]
	v_mfma_f32_16x16x32_bf16 v[34:37], v[166:169], v[188:191], v[34:37]
	v_mfma_f32_16x16x32_bf16 v[22:25], v[158:161], v[196:199], v[22:25]
	v_mfma_f32_16x16x32_bf16 v[18:21], v[166:169], v[196:199], v[18:21]
	v_mfma_f32_16x16x32_bf16 v[6:9], v[158:161], v[204:207], v[6:9]
	v_mfma_f32_16x16x32_bf16 v[2:5], v[166:169], v[204:207], v[2:5]
	v_mfma_f32_16x16x32_bf16 v[54:57], v[162:165], v[184:187], v[54:57]
	v_mfma_f32_16x16x32_bf16 v[50:53], v[172:175], v[184:187], v[50:53]
	v_mfma_f32_16x16x32_bf16 v[38:41], v[162:165], v[192:195], v[38:41]
	v_mfma_f32_16x16x32_bf16 v[34:37], v[172:175], v[192:195], v[34:37]
	v_mfma_f32_16x16x32_bf16 v[22:25], v[162:165], v[200:203], v[22:25]
	v_mfma_f32_16x16x32_bf16 v[18:21], v[172:175], v[200:203], v[18:21]
	v_mfma_f32_16x16x32_bf16 v[6:9], v[162:165], v[212:215], v[6:9]
	v_mfma_f32_16x16x32_bf16 v[2:5], v[172:175], v[212:215], v[2:5]
	s_setprio 0
	s_barrier
	s_add_u32 s1, s1, 0x100
	s_addc_u32 s5, s5, 0
	s_add_u32 s10, s10, 0x100
	s_addc_u32 s11, s11, 0
	s_cmp_ge_i32 s7, s73
	s_mov_b32 s6, s7
	s_cbranch_scc0 .LBB0_522
	v_mov_b64_e32 v[224:225], v[210:211]

.LBB0_787:
	s_add_i32 s25, s12, 2
	s_add_u32 s33, s10, 0x80
	s_addc_u32 s13, s11, 0
	s_add_i32 s36, 0, 0x10000
	s_cmp_eq_u32 s20, s12
	s_cselect_b32 s13, s45, s13
	s_cselect_b32 s12, s44, s33
	v_add_u32_e32 v146, s36, v149
	s_cselect_b32 s35, s61, s24
	s_cselect_b32 s34, s60, s1
	s_add_i32 s33, 0, 0x14000
	ds_read_b128 v[142:145], v146
	ds_read_b128 v[152:155], v146 offset:1024
	ds_read_b128 v[156:159], v146 offset:2048
	ds_read_b128 v[160:163], v146 offset:3072
	v_add_u32_e32 v146, s33, v149
	ds_read_b128 v[164:167], v146
	ds_read_b128 v[168:171], v146 offset:1024
	ds_read_b128 v[172:175], v146 offset:2048
	ds_read_b128 v[176:179], v146 offset:3072
	v_lshl_add_u64 v[146:147], s[10:11], 0, v[138:139]
	s_add_i32 m0, s5, 0xc000
	ds_read_b128 v[180:183], v150
	ds_read_b128 v[184:187], v150 offset:1024
	ds_read_b128 v[188:191], v150 offset:2048
	ds_read_b128 v[192:195], v150 offset:3072
	ds_read_b128 v[196:199], v150 offset:4096
	ds_read_b128 v[200:203], v150 offset:5120
	ds_read_b128 v[204:207], v150 offset:6144
	ds_read_b128 v[212:215], v150 offset:7168
	global_load_lds_dwordx4 v[146:147], off
	v_lshl_add_u64 v[146:147], s[10:11], 0, v[140:141]
	s_add_i32 m0, s5, 0xe000
	s_nop 0
	global_load_lds_dwordx4 v[146:147], off
	s_waitcnt vmcnt(8)
	s_waitcnt lgkmcnt(0)
	s_barrier
	s_setprio 1
	v_mfma_f32_16x16x32_bf16 v[126:129], v[142:145], v[180:183], v[126:129]
	v_mfma_f32_16x16x32_bf16 v[122:125], v[156:159], v[180:183], v[122:125]
	v_mfma_f32_16x16x32_bf16 v[110:113], v[142:145], v[188:191], v[110:113]
	v_mfma_f32_16x16x32_bf16 v[106:109], v[156:159], v[188:191], v[106:109]
	v_mfma_f32_16x16x32_bf16 v[94:97], v[142:145], v[196:199], v[94:97]
	v_mfma_f32_16x16x32_bf16 v[90:93], v[156:159], v[196:199], v[90:93]
	v_mfma_f32_16x16x32_bf16 v[78:81], v[142:145], v[204:207], v[78:81]
	v_mfma_f32_16x16x32_bf16 v[74:77], v[156:159], v[204:207], v[74:77]
	v_mfma_f32_16x16x32_bf16 v[126:129], v[152:155], v[184:187], v[126:129]
	v_mfma_f32_16x16x32_bf16 v[122:125], v[160:163], v[184:187], v[122:125]
	v_mfma_f32_16x16x32_bf16 v[110:113], v[152:155], v[192:195], v[110:113]
	v_mfma_f32_16x16x32_bf16 v[106:109], v[160:163], v[192:195], v[106:109]
	v_mfma_f32_16x16x32_bf16 v[94:97], v[152:155], v[200:203], v[94:97]
	v_mfma_f32_16x16x32_bf16 v[90:93], v[160:163], v[200:203], v[90:93]
	v_mfma_f32_16x16x32_bf16 v[78:81], v[152:155], v[212:215], v[78:81]
	v_mfma_f32_16x16x32_bf16 v[74:77], v[160:163], v[212:215], v[74:77]
	s_setprio 0
	s_setprio 1
	v_mfma_f32_16x16x32_bf16 v[118:121], v[164:167], v[180:183], v[118:121]
	v_mfma_f32_16x16x32_bf16 v[114:117], v[172:175], v[180:183], v[114:117]
	v_mfma_f32_16x16x32_bf16 v[102:105], v[164:167], v[188:191], v[102:105]
	v_mfma_f32_16x16x32_bf16 v[98:101], v[172:175], v[188:191], v[98:101]
	v_mfma_f32_16x16x32_bf16 v[86:89], v[164:167], v[196:199], v[86:89]
	v_mfma_f32_16x16x32_bf16 v[82:85], v[172:175], v[196:199], v[82:85]
	v_mfma_f32_16x16x32_bf16 v[70:73], v[164:167], v[204:207], v[70:73]
	v_mfma_f32_16x16x32_bf16 v[66:69], v[172:175], v[204:207], v[66:69]
	v_mfma_f32_16x16x32_bf16 v[118:121], v[168:171], v[184:187], v[118:121]
	v_mfma_f32_16x16x32_bf16 v[114:117], v[176:179], v[184:187], v[114:117]
	v_mfma_f32_16x16x32_bf16 v[102:105], v[168:171], v[192:195], v[102:105]
	v_mfma_f32_16x16x32_bf16 v[98:101], v[176:179], v[192:195], v[98:101]
	v_mfma_f32_16x16x32_bf16 v[86:89], v[168:171], v[200:203], v[86:89]
	v_mfma_f32_16x16x32_bf16 v[82:85], v[176:179], v[200:203], v[82:85]
	v_mfma_f32_16x16x32_bf16 v[70:73], v[168:171], v[212:215], v[70:73]
	v_mfma_f32_16x16x32_bf16 v[66:69], v[176:179], v[212:215], v[66:69]
	s_setprio 0
	s_barrier
	s_add_i32 s36, s36, s4
	v_lshl_add_u64 v[146:147], s[34:35], 0, v[136:137]
	s_mov_b32 m0, s36
	ds_read_b128 v[180:183], v150 offset:16384
	ds_read_b128 v[184:187], v150 offset:17408
	ds_read_b128 v[188:191], v150 offset:18432
	ds_read_b128 v[192:195], v150 offset:19456
	ds_read_b128 v[196:199], v150 offset:20480
	ds_read_b128 v[200:203], v150 offset:21504
	ds_read_b128 v[204:207], v150 offset:22528
	ds_read_b128 v[212:215], v150 offset:23552
	global_load_lds_dwordx4 v[146:147], off
	s_add_i32 m0, s36, 0x2000
	v_lshl_add_u64 v[208:209], s[34:35], 0, v[132:133]
	s_add_u32 s34, s34, s50
	s_addc_u32 s35, s35, s51
	s_add_i32 s33, s33, s4
	global_load_lds_dwordx4 v[208:209], off
	v_lshl_add_u64 v[210:211], s[34:35], 0, v[136:137]
	s_mov_b32 m0, s33
	v_lshl_add_u64 v[216:217], s[34:35], 0, v[132:133]
	global_load_lds_dwordx4 v[210:211], off
	s_add_i32 m0, s33, 0x2000
	v_lshl_add_u64 v[218:219], s[12:13], 0, v[134:135]
	global_load_lds_dwordx4 v[216:217], off
	s_mov_b32 m0, s5
	v_lshl_add_u64 v[220:221], s[12:13], 0, v[130:131]
	global_load_lds_dwordx4 v[218:219], off
	s_mov_b32 m0, s6
	s_nop 0
	global_load_lds_dwordx4 v[220:221], off
	s_waitcnt vmcnt(8)
	s_waitcnt lgkmcnt(0)
	s_barrier
	s_setprio 1
	v_mfma_f32_16x16x32_bf16 v[62:65], v[142:145], v[180:183], v[62:65]
	v_mfma_f32_16x16x32_bf16 v[58:61], v[156:159], v[180:183], v[58:61]
	v_mfma_f32_16x16x32_bf16 v[46:49], v[142:145], v[188:191], v[46:49]
	v_mfma_f32_16x16x32_bf16 v[42:45], v[156:159], v[188:191], v[42:45]
	v_mfma_f32_16x16x32_bf16 v[30:33], v[142:145], v[196:199], v[30:33]
	v_mfma_f32_16x16x32_bf16 v[26:29], v[156:159], v[196:199], v[26:29]
	v_mfma_f32_16x16x32_bf16 v[14:17], v[142:145], v[204:207], v[14:17]
	v_mfma_f32_16x16x32_bf16 v[10:13], v[156:159], v[204:207], v[10:13]
	v_mfma_f32_16x16x32_bf16 v[62:65], v[152:155], v[184:187], v[62:65]
	v_mfma_f32_16x16x32_bf16 v[58:61], v[160:163], v[184:187], v[58:61]
	v_mfma_f32_16x16x32_bf16 v[46:49], v[152:155], v[192:195], v[46:49]
	v_mfma_f32_16x16x32_bf16 v[42:45], v[160:163], v[192:195], v[42:45]
	v_mfma_f32_16x16x32_bf16 v[30:33], v[152:155], v[200:203], v[30:33]
	v_mfma_f32_16x16x32_bf16 v[26:29], v[160:163], v[200:203], v[26:29]
	v_mfma_f32_16x16x32_bf16 v[14:17], v[152:155], v[212:215], v[14:17]
	v_mfma_f32_16x16x32_bf16 v[10:13], v[160:163], v[212:215], v[10:13]
	s_setprio 0
	s_setprio 1
	v_mfma_f32_16x16x32_bf16 v[54:57], v[164:167], v[180:183], v[54:57]
	v_mfma_f32_16x16x32_bf16 v[50:53], v[172:175], v[180:183], v[50:53]
	v_mfma_f32_16x16x32_bf16 v[38:41], v[164:167], v[188:191], v[38:41]
	v_mfma_f32_16x16x32_bf16 v[34:37], v[172:175], v[188:191], v[34:37]
	v_mfma_f32_16x16x32_bf16 v[22:25], v[164:167], v[196:199], v[22:25]
	v_mfma_f32_16x16x32_bf16 v[18:21], v[172:175], v[196:199], v[18:21]
	v_mfma_f32_16x16x32_bf16 v[6:9], v[164:167], v[204:207], v[6:9]
	v_mfma_f32_16x16x32_bf16 v[2:5], v[172:175], v[204:207], v[2:5]
	v_mfma_f32_16x16x32_bf16 v[54:57], v[168:171], v[184:187], v[54:57]
	v_mfma_f32_16x16x32_bf16 v[50:53], v[176:179], v[184:187], v[50:53]
	v_mfma_f32_16x16x32_bf16 v[38:41], v[168:171], v[192:195], v[38:41]
	v_mfma_f32_16x16x32_bf16 v[34:37], v[176:179], v[192:195], v[34:37]
	v_mfma_f32_16x16x32_bf16 v[22:25], v[168:171], v[200:203], v[22:25]
	v_mfma_f32_16x16x32_bf16 v[18:21], v[176:179], v[200:203], v[18:21]
	v_mfma_f32_16x16x32_bf16 v[6:9], v[168:171], v[212:215], v[6:9]
	v_mfma_f32_16x16x32_bf16 v[2:5], v[176:179], v[212:215], v[2:5]
	s_setprio 0
	s_barrier
	s_add_i32 s33, 0, 0x18000
	v_add_u32_e32 v151, s33, v149
	s_add_i32 s34, 0, 0x1c000
	ds_read_b128 v[142:145], v151
	ds_read_b128 v[152:155], v151 offset:1024
	ds_read_b128 v[156:159], v151 offset:2048
	ds_read_b128 v[160:163], v151 offset:3072
	v_add_u32_e32 v151, s34, v149
	ds_read_b128 v[164:167], v151
	ds_read_b128 v[168:171], v151 offset:1024
	ds_read_b128 v[172:175], v151 offset:2048
	ds_read_b128 v[176:179], v151 offset:3072
	s_add_u32 s12, s12, s50
	s_addc_u32 s13, s13, s51
	s_mov_b32 m0, s7
	v_lshl_add_u64 v[222:223], s[12:13], 0, v[134:135]
	ds_read_b128 v[180:183], v150 offset:32768
	ds_read_b128 v[184:187], v150 offset:33792
	ds_read_b128 v[188:191], v150 offset:34816
	ds_read_b128 v[192:195], v150 offset:35840
	ds_read_b128 v[196:199], v150 offset:36864
	ds_read_b128 v[200:203], v150 offset:37888
	ds_read_b128 v[204:207], v150 offset:38912
	ds_read_b128 v[212:215], v150 offset:39936
	global_load_lds_dwordx4 v[222:223], off
	v_lshl_add_u64 v[222:223], s[12:13], 0, v[130:131]
	s_mov_b32 m0, s8
	s_nop 0
	global_load_lds_dwordx4 v[222:223], off
	s_waitcnt vmcnt(8)
	s_waitcnt lgkmcnt(0)
	s_barrier
	s_setprio 1
	v_mfma_f32_16x16x32_bf16 v[126:129], v[142:145], v[180:183], v[126:129]
	v_mfma_f32_16x16x32_bf16 v[122:125], v[156:159], v[180:183], v[122:125]
	v_mfma_f32_16x16x32_bf16 v[110:113], v[142:145], v[188:191], v[110:113]
	v_mfma_f32_16x16x32_bf16 v[106:109], v[156:159], v[188:191], v[106:109]
	v_mfma_f32_16x16x32_bf16 v[94:97], v[142:145], v[196:199], v[94:97]
	v_mfma_f32_16x16x32_bf16 v[90:93], v[156:159], v[196:199], v[90:93]
	v_mfma_f32_16x16x32_bf16 v[78:81], v[142:145], v[204:207], v[78:81]
	v_mfma_f32_16x16x32_bf16 v[74:77], v[156:159], v[204:207], v[74:77]
	v_mfma_f32_16x16x32_bf16 v[126:129], v[152:155], v[184:187], v[126:129]
	v_mfma_f32_16x16x32_bf16 v[122:125], v[160:163], v[184:187], v[122:125]
	v_mfma_f32_16x16x32_bf16 v[110:113], v[152:155], v[192:195], v[110:113]
	v_mfma_f32_16x16x32_bf16 v[106:109], v[160:163], v[192:195], v[106:109]
	v_mfma_f32_16x16x32_bf16 v[94:97], v[152:155], v[200:203], v[94:97]
	v_mfma_f32_16x16x32_bf16 v[90:93], v[160:163], v[200:203], v[90:93]
	v_mfma_f32_16x16x32_bf16 v[78:81], v[152:155], v[212:215], v[78:81]
	v_mfma_f32_16x16x32_bf16 v[74:77], v[160:163], v[212:215], v[74:77]
	s_setprio 0
	s_setprio 1
	v_mfma_f32_16x16x32_bf16 v[118:121], v[164:167], v[180:183], v[118:121]
	v_mfma_f32_16x16x32_bf16 v[114:117], v[172:175], v[180:183], v[114:117]
	v_mfma_f32_16x16x32_bf16 v[102:105], v[164:167], v[188:191], v[102:105]
	v_mfma_f32_16x16x32_bf16 v[98:101], v[172:175], v[188:191], v[98:101]
	v_mfma_f32_16x16x32_bf16 v[86:89], v[164:167], v[196:199], v[86:89]
	v_mfma_f32_16x16x32_bf16 v[82:85], v[172:175], v[196:199], v[82:85]
	v_mfma_f32_16x16x32_bf16 v[70:73], v[164:167], v[204:207], v[70:73]
	v_mfma_f32_16x16x32_bf16 v[66:69], v[172:175], v[204:207], v[66:69]
	v_mfma_f32_16x16x32_bf16 v[118:121], v[168:171], v[184:187], v[118:121]
	v_mfma_f32_16x16x32_bf16 v[114:117], v[176:179], v[184:187], v[114:117]
	v_mfma_f32_16x16x32_bf16 v[102:105], v[168:171], v[192:195], v[102:105]
	v_mfma_f32_16x16x32_bf16 v[98:101], v[176:179], v[192:195], v[98:101]
	v_mfma_f32_16x16x32_bf16 v[86:89], v[168:171], v[200:203], v[86:89]
	v_mfma_f32_16x16x32_bf16 v[82:85], v[176:179], v[200:203], v[82:85]
	v_mfma_f32_16x16x32_bf16 v[70:73], v[168:171], v[212:215], v[70:73]
	v_mfma_f32_16x16x32_bf16 v[66:69], v[176:179], v[212:215], v[66:69]
	s_setprio 0
	s_barrier
	s_add_i32 s12, s33, s4
	v_lshl_add_u64 v[146:147], v[146:147], 0, s[28:29]
	s_mov_b32 m0, s12
	ds_read_b128 v[180:183], v150 offset:49152
	ds_read_b128 v[184:187], v150 offset:50176
	ds_read_b128 v[188:191], v150 offset:51200
	ds_read_b128 v[192:195], v150 offset:52224
	ds_read_b128 v[196:199], v150 offset:53248
	ds_read_b128 v[200:203], v150 offset:54272
	ds_read_b128 v[204:207], v150 offset:55296
	ds_read_b128 v[212:215], v150 offset:56320
	global_load_lds_dwordx4 v[146:147], off
	v_lshl_add_u64 v[146:147], v[208:209], 0, s[28:29]
	s_add_i32 m0, s12, 0x2000
	s_add_i32 s12, s34, s4
	global_load_lds_dwordx4 v[146:147], off
	v_lshl_add_u64 v[146:147], v[210:211], 0, s[28:29]
	s_mov_b32 m0, s12
	s_nop 0
	global_load_lds_dwordx4 v[146:147], off
	v_lshl_add_u64 v[146:147], v[216:217], 0, s[28:29]
	s_add_i32 m0, s12, 0x2000
	s_nop 0
	global_load_lds_dwordx4 v[146:147], off
	v_lshl_add_u64 v[146:147], v[218:219], 0, s[28:29]
	s_mov_b32 m0, s9
	s_nop 0
	global_load_lds_dwordx4 v[146:147], off
	v_lshl_add_u64 v[146:147], v[220:221], 0, s[28:29]
	s_mov_b32 m0, s14
	s_nop 0
	global_load_lds_dwordx4 v[146:147], off
	s_waitcnt vmcnt(8)
	s_waitcnt lgkmcnt(0)
	s_barrier
	s_setprio 1
	v_mfma_f32_16x16x32_bf16 v[62:65], v[142:145], v[180:183], v[62:65]
	v_mfma_f32_16x16x32_bf16 v[58:61], v[156:159], v[180:183], v[58:61]
	v_mfma_f32_16x16x32_bf16 v[46:49], v[142:145], v[188:191], v[46:49]
	v_mfma_f32_16x16x32_bf16 v[42:45], v[156:159], v[188:191], v[42:45]
	v_mfma_f32_16x16x32_bf16 v[30:33], v[142:145], v[196:199], v[30:33]
	v_mfma_f32_16x16x32_bf16 v[26:29], v[156:159], v[196:199], v[26:29]
	v_mfma_f32_16x16x32_bf16 v[14:17], v[142:145], v[204:207], v[14:17]
	v_mfma_f32_16x16x32_bf16 v[10:13], v[156:159], v[204:207], v[10:13]
	v_mfma_f32_16x16x32_bf16 v[62:65], v[152:155], v[184:187], v[62:65]
	v_mfma_f32_16x16x32_bf16 v[58:61], v[160:163], v[184:187], v[58:61]
	v_mfma_f32_16x16x32_bf16 v[46:49], v[152:155], v[192:195], v[46:49]
	v_mfma_f32_16x16x32_bf16 v[42:45], v[160:163], v[192:195], v[42:45]
	v_mfma_f32_16x16x32_bf16 v[30:33], v[152:155], v[200:203], v[30:33]
	v_mfma_f32_16x16x32_bf16 v[26:29], v[160:163], v[200:203], v[26:29]
	v_mfma_f32_16x16x32_bf16 v[14:17], v[152:155], v[212:215], v[14:17]
	v_mfma_f32_16x16x32_bf16 v[10:13], v[160:163], v[212:215], v[10:13]
	s_setprio 0
	s_setprio 1
	v_mfma_f32_16x16x32_bf16 v[54:57], v[164:167], v[180:183], v[54:57]
	v_mfma_f32_16x16x32_bf16 v[50:53], v[172:175], v[180:183], v[50:53]
	v_mfma_f32_16x16x32_bf16 v[38:41], v[164:167], v[188:191], v[38:41]
	v_mfma_f32_16x16x32_bf16 v[34:37], v[172:175], v[188:191], v[34:37]
	v_mfma_f32_16x16x32_bf16 v[22:25], v[164:167], v[196:199], v[22:25]
	v_mfma_f32_16x16x32_bf16 v[18:21], v[172:175], v[196:199], v[18:21]
	v_mfma_f32_16x16x32_bf16 v[6:9], v[164:167], v[204:207], v[6:9]
	v_mfma_f32_16x16x32_bf16 v[2:5], v[172:175], v[204:207], v[2:5]
	v_mfma_f32_16x16x32_bf16 v[54:57], v[168:171], v[184:187], v[54:57]
	v_mfma_f32_16x16x32_bf16 v[50:53], v[176:179], v[184:187], v[50:53]
	v_mfma_f32_16x16x32_bf16 v[38:41], v[168:171], v[192:195], v[38:41]
	v_mfma_f32_16x16x32_bf16 v[34:37], v[176:179], v[192:195], v[34:37]
	v_mfma_f32_16x16x32_bf16 v[22:25], v[168:171], v[200:203], v[22:25]
	v_mfma_f32_16x16x32_bf16 v[18:21], v[176:179], v[200:203], v[18:21]
	v_mfma_f32_16x16x32_bf16 v[6:9], v[168:171], v[212:215], v[6:9]
	v_mfma_f32_16x16x32_bf16 v[2:5], v[176:179], v[212:215], v[2:5]
	s_setprio 0
	s_barrier
	s_add_u32 s1, s1, 0x100
	s_addc_u32 s24, s24, 0
	s_add_u32 s10, s10, 0x100
	s_addc_u32 s11, s11, 0
	s_cmp_ge_i32 s25, s18
	s_mov_b32 s12, s25
	s_cbranch_scc0 .LBB0_787

.LBB0_931:
	s_add_i32 s24, s10, 2
	s_add_u32 s25, s0, 0x80
	s_addc_u32 s11, s1, 0
	s_add_i32 s38, 0, 0x10000
	s_cmp_eq_u32 s30, s10
	s_cselect_b32 s11, s91, s11
	s_cselect_b32 s10, s90, s25
	s_cselect_b32 s27, s51, s13
	s_cselect_b32 s26, s50, s12
	s_add_i32 s25, 0, 0x14000
	v_add_u32_e32 v142, s38, v201
	v_add_u32_e32 v158, s25, v201
	ds_read_b128 v[130:133], v142
	ds_read_b128 v[134:137], v142 offset:1024
	ds_read_b128 v[138:141], v142 offset:2048
	ds_read_b128 v[142:145], v142 offset:3072
	ds_read_b128 v[146:149], v158
	ds_read_b128 v[150:153], v158 offset:1024
	ds_read_b128 v[154:157], v158 offset:2048
	ds_read_b128 v[158:161], v158 offset:3072
	v_lshl_add_u64 v[198:199], s[0:1], 0, v[186:187]
	s_add_i32 m0, s7, 0xc000
	ds_read_b128 v[162:165], v202
	ds_read_b128 v[166:169], v202 offset:1024
	ds_read_b128 v[170:173], v202 offset:2048
	ds_read_b128 v[174:177], v202 offset:3072
	ds_read_b128 v[190:193], v202 offset:4096
	ds_read_b128 v[194:197], v202 offset:5120
	ds_read_b128 v[204:207], v202 offset:6144
	ds_read_b128 v[212:215], v202 offset:7168
	global_load_lds_dwordx4 v[198:199], off
	v_lshl_add_u64 v[198:199], s[0:1], 0, v[188:189]
	s_add_i32 m0, s7, 0xe000
	s_nop 0
	global_load_lds_dwordx4 v[198:199], off
	s_waitcnt vmcnt(8)
	s_waitcnt lgkmcnt(0)
	s_barrier
	s_setprio 1
	v_mfma_f32_16x16x32_bf16 v[94:97], v[130:133], v[162:165], v[94:97]
	v_mfma_f32_16x16x32_bf16 v[30:33], v[138:141], v[162:165], v[30:33]
	v_mfma_f32_16x16x32_bf16 v[82:85], v[130:133], v[170:173], v[82:85]
	v_mfma_f32_16x16x32_bf16 v[22:25], v[138:141], v[170:173], v[22:25]
	v_mfma_f32_16x16x32_bf16 v[114:117], v[130:133], v[190:193], v[114:117]
	v_mfma_f32_16x16x32_bf16 v[42:45], v[138:141], v[190:193], v[42:45]
	v_mfma_f32_16x16x32_bf16 v[122:125], v[130:133], v[204:207], v[122:125]
	v_mfma_f32_16x16x32_bf16 v[58:61], v[138:141], v[204:207], v[58:61]
	v_mfma_f32_16x16x32_bf16 v[94:97], v[134:137], v[166:169], v[94:97]
	v_mfma_f32_16x16x32_bf16 v[30:33], v[142:145], v[166:169], v[30:33]
	v_mfma_f32_16x16x32_bf16 v[82:85], v[134:137], v[174:177], v[82:85]
	v_mfma_f32_16x16x32_bf16 v[22:25], v[142:145], v[174:177], v[22:25]
	v_mfma_f32_16x16x32_bf16 v[114:117], v[134:137], v[194:197], v[114:117]
	v_mfma_f32_16x16x32_bf16 v[42:45], v[142:145], v[194:197], v[42:45]
	v_mfma_f32_16x16x32_bf16 v[122:125], v[134:137], v[212:215], v[122:125]
	v_mfma_f32_16x16x32_bf16 v[58:61], v[142:145], v[212:215], v[58:61]
	s_setprio 0
	s_setprio 1
	v_mfma_f32_16x16x32_bf16 v[90:93], v[146:149], v[162:165], v[90:93]
	v_mfma_f32_16x16x32_bf16 v[26:29], v[154:157], v[162:165], v[26:29]
	v_mfma_f32_16x16x32_bf16 v[78:81], v[146:149], v[170:173], v[78:81]
	v_mfma_f32_16x16x32_bf16 v[18:21], v[154:157], v[170:173], v[18:21]
	v_mfma_f32_16x16x32_bf16 v[118:121], v[146:149], v[190:193], v[118:121]
	v_mfma_f32_16x16x32_bf16 v[54:57], v[154:157], v[190:193], v[54:57]
	v_mfma_f32_16x16x32_bf16 v[126:129], v[146:149], v[204:207], v[126:129]
	v_mfma_f32_16x16x32_bf16 v[62:65], v[154:157], v[204:207], v[62:65]
	v_mfma_f32_16x16x32_bf16 v[90:93], v[150:153], v[166:169], v[90:93]
	v_mfma_f32_16x16x32_bf16 v[26:29], v[158:161], v[166:169], v[26:29]
	v_mfma_f32_16x16x32_bf16 v[78:81], v[150:153], v[174:177], v[78:81]
	v_mfma_f32_16x16x32_bf16 v[18:21], v[158:161], v[174:177], v[18:21]
	v_mfma_f32_16x16x32_bf16 v[118:121], v[150:153], v[194:197], v[118:121]
	v_mfma_f32_16x16x32_bf16 v[54:57], v[158:161], v[194:197], v[54:57]
	v_mfma_f32_16x16x32_bf16 v[126:129], v[150:153], v[212:215], v[126:129]
	v_mfma_f32_16x16x32_bf16 v[62:65], v[158:161], v[212:215], v[62:65]
	s_setprio 0
	s_barrier
	s_add_i32 s38, s38, s6
	v_lshl_add_u64 v[198:199], s[26:27], 0, v[178:179]
	s_mov_b32 m0, s38
	ds_read_b128 v[162:165], v202 offset:16384
	ds_read_b128 v[166:169], v202 offset:17408
	ds_read_b128 v[170:173], v202 offset:18432
	ds_read_b128 v[174:177], v202 offset:19456
	ds_read_b128 v[190:193], v202 offset:20480
	ds_read_b128 v[194:197], v202 offset:21504
	ds_read_b128 v[204:207], v202 offset:22528
	ds_read_b128 v[212:215], v202 offset:23552
	global_load_lds_dwordx4 v[198:199], off
	s_add_i32 m0, s38, 0x2000
	v_lshl_add_u64 v[208:209], s[26:27], 0, v[182:183]
	s_add_u32 s26, s26, s56
	s_addc_u32 s27, s27, s57
	s_add_i32 s25, s25, s6
	global_load_lds_dwordx4 v[208:209], off
	v_lshl_add_u64 v[210:211], s[26:27], 0, v[178:179]
	s_mov_b32 m0, s25
	v_lshl_add_u64 v[216:217], s[26:27], 0, v[182:183]
	global_load_lds_dwordx4 v[210:211], off
	s_add_i32 m0, s25, 0x2000
	v_lshl_add_u64 v[218:219], s[10:11], 0, v[180:181]
	global_load_lds_dwordx4 v[216:217], off
	s_mov_b32 m0, s7
	v_lshl_add_u64 v[220:221], s[10:11], 0, v[184:185]
	global_load_lds_dwordx4 v[218:219], off
	s_mov_b32 m0, s36
	s_nop 0
	global_load_lds_dwordx4 v[220:221], off
	s_waitcnt vmcnt(8)
	s_waitcnt lgkmcnt(0)
	s_barrier
	s_setprio 1
	v_mfma_f32_16x16x32_bf16 v[70:73], v[130:133], v[162:165], v[70:73]
	v_mfma_f32_16x16x32_bf16 v[14:17], v[138:141], v[162:165], v[14:17]
	v_mfma_f32_16x16x32_bf16 v[50:53], v[130:133], v[170:173], v[50:53]
	v_mfma_f32_16x16x32_bf16 v[6:9], v[138:141], v[170:173], v[6:9]
	v_mfma_f32_16x16x32_bf16 v[106:109], v[130:133], v[190:193], v[106:109]
	v_mfma_f32_16x16x32_bf16 v[34:37], v[138:141], v[190:193], v[34:37]
	v_mfma_f32_16x16x32_bf16 v[102:105], v[130:133], v[204:207], v[102:105]
	v_mfma_f32_16x16x32_bf16 v[74:77], v[138:141], v[204:207], v[74:77]
	v_mfma_f32_16x16x32_bf16 v[70:73], v[134:137], v[166:169], v[70:73]
	v_mfma_f32_16x16x32_bf16 v[14:17], v[142:145], v[166:169], v[14:17]
	v_mfma_f32_16x16x32_bf16 v[50:53], v[134:137], v[174:177], v[50:53]
	v_mfma_f32_16x16x32_bf16 v[6:9], v[142:145], v[174:177], v[6:9]
	v_mfma_f32_16x16x32_bf16 v[106:109], v[134:137], v[194:197], v[106:109]
	v_mfma_f32_16x16x32_bf16 v[34:37], v[142:145], v[194:197], v[34:37]
	v_mfma_f32_16x16x32_bf16 v[102:105], v[134:137], v[212:215], v[102:105]
	v_mfma_f32_16x16x32_bf16 v[74:77], v[142:145], v[212:215], v[74:77]
	s_setprio 0
	s_setprio 1
	v_mfma_f32_16x16x32_bf16 v[66:69], v[146:149], v[162:165], v[66:69]
	v_mfma_f32_16x16x32_bf16 v[10:13], v[154:157], v[162:165], v[10:13]
	v_mfma_f32_16x16x32_bf16 v[46:49], v[146:149], v[170:173], v[46:49]
	v_mfma_f32_16x16x32_bf16 v[2:5], v[154:157], v[170:173], v[2:5]
	v_mfma_f32_16x16x32_bf16 v[110:113], v[146:149], v[190:193], v[110:113]
	v_mfma_f32_16x16x32_bf16 v[38:41], v[154:157], v[190:193], v[38:41]
	v_mfma_f32_16x16x32_bf16 v[98:101], v[146:149], v[204:207], v[98:101]
	v_mfma_f32_16x16x32_bf16 v[86:89], v[154:157], v[204:207], v[86:89]
	v_mfma_f32_16x16x32_bf16 v[66:69], v[150:153], v[166:169], v[66:69]
	v_mfma_f32_16x16x32_bf16 v[10:13], v[158:161], v[166:169], v[10:13]
	v_mfma_f32_16x16x32_bf16 v[46:49], v[150:153], v[174:177], v[46:49]
	v_mfma_f32_16x16x32_bf16 v[2:5], v[158:161], v[174:177], v[2:5]
	v_mfma_f32_16x16x32_bf16 v[110:113], v[150:153], v[194:197], v[110:113]
	v_mfma_f32_16x16x32_bf16 v[38:41], v[158:161], v[194:197], v[38:41]
	v_mfma_f32_16x16x32_bf16 v[98:101], v[150:153], v[212:215], v[98:101]
	v_mfma_f32_16x16x32_bf16 v[86:89], v[158:161], v[212:215], v[86:89]
	s_setprio 0
	s_barrier
	s_add_i32 s25, 0, 0x18000
	s_add_i32 s26, 0, 0x1c000
	v_add_u32_e32 v142, s25, v201
	v_add_u32_e32 v158, s26, v201
	ds_read_b128 v[130:133], v142
	ds_read_b128 v[134:137], v142 offset:1024
	ds_read_b128 v[138:141], v142 offset:2048
	ds_read_b128 v[142:145], v142 offset:3072
	ds_read_b128 v[146:149], v158
	ds_read_b128 v[150:153], v158 offset:1024
	ds_read_b128 v[154:157], v158 offset:2048
	ds_read_b128 v[158:161], v158 offset:3072
	s_add_u32 s10, s10, s56
	s_addc_u32 s11, s11, s57
	s_mov_b32 m0, s96
	v_lshl_add_u64 v[222:223], s[10:11], 0, v[180:181]
	ds_read_b128 v[162:165], v202 offset:32768
	ds_read_b128 v[166:169], v202 offset:33792
	ds_read_b128 v[170:173], v202 offset:34816
	ds_read_b128 v[174:177], v202 offset:35840
	ds_read_b128 v[190:193], v202 offset:36864
	ds_read_b128 v[194:197], v202 offset:37888
	ds_read_b128 v[204:207], v202 offset:38912
	ds_read_b128 v[212:215], v202 offset:39936
	global_load_lds_dwordx4 v[222:223], off
	v_lshl_add_u64 v[222:223], s[10:11], 0, v[184:185]
	s_mov_b32 m0, s97
	s_nop 0
	global_load_lds_dwordx4 v[222:223], off
	s_waitcnt vmcnt(8)
	s_waitcnt lgkmcnt(0)
	s_barrier
	s_setprio 1
	v_mfma_f32_16x16x32_bf16 v[94:97], v[130:133], v[162:165], v[94:97]
	v_mfma_f32_16x16x32_bf16 v[30:33], v[138:141], v[162:165], v[30:33]
	v_mfma_f32_16x16x32_bf16 v[82:85], v[130:133], v[170:173], v[82:85]
	v_mfma_f32_16x16x32_bf16 v[22:25], v[138:141], v[170:173], v[22:25]
	v_mfma_f32_16x16x32_bf16 v[114:117], v[130:133], v[190:193], v[114:117]
	v_mfma_f32_16x16x32_bf16 v[42:45], v[138:141], v[190:193], v[42:45]
	v_mfma_f32_16x16x32_bf16 v[122:125], v[130:133], v[204:207], v[122:125]
	v_mfma_f32_16x16x32_bf16 v[58:61], v[138:141], v[204:207], v[58:61]
	v_mfma_f32_16x16x32_bf16 v[94:97], v[134:137], v[166:169], v[94:97]
	v_mfma_f32_16x16x32_bf16 v[30:33], v[142:145], v[166:169], v[30:33]
	v_mfma_f32_16x16x32_bf16 v[82:85], v[134:137], v[174:177], v[82:85]
	v_mfma_f32_16x16x32_bf16 v[22:25], v[142:145], v[174:177], v[22:25]
	v_mfma_f32_16x16x32_bf16 v[114:117], v[134:137], v[194:197], v[114:117]
	v_mfma_f32_16x16x32_bf16 v[42:45], v[142:145], v[194:197], v[42:45]
	v_mfma_f32_16x16x32_bf16 v[122:125], v[134:137], v[212:215], v[122:125]
	v_mfma_f32_16x16x32_bf16 v[58:61], v[142:145], v[212:215], v[58:61]
	s_setprio 0
	s_setprio 1
	v_mfma_f32_16x16x32_bf16 v[90:93], v[146:149], v[162:165], v[90:93]
	v_mfma_f32_16x16x32_bf16 v[26:29], v[154:157], v[162:165], v[26:29]
	v_mfma_f32_16x16x32_bf16 v[78:81], v[146:149], v[170:173], v[78:81]
	v_mfma_f32_16x16x32_bf16 v[18:21], v[154:157], v[170:173], v[18:21]
	v_mfma_f32_16x16x32_bf16 v[118:121], v[146:149], v[190:193], v[118:121]
	v_mfma_f32_16x16x32_bf16 v[54:57], v[154:157], v[190:193], v[54:57]
	v_mfma_f32_16x16x32_bf16 v[126:129], v[146:149], v[204:207], v[126:129]
	v_mfma_f32_16x16x32_bf16 v[62:65], v[154:157], v[204:207], v[62:65]
	v_mfma_f32_16x16x32_bf16 v[90:93], v[150:153], v[166:169], v[90:93]
	v_mfma_f32_16x16x32_bf16 v[26:29], v[158:161], v[166:169], v[26:29]
	v_mfma_f32_16x16x32_bf16 v[78:81], v[150:153], v[174:177], v[78:81]
	v_mfma_f32_16x16x32_bf16 v[18:21], v[158:161], v[174:177], v[18:21]
	v_mfma_f32_16x16x32_bf16 v[118:121], v[150:153], v[194:197], v[118:121]
	v_mfma_f32_16x16x32_bf16 v[54:57], v[158:161], v[194:197], v[54:57]
	v_mfma_f32_16x16x32_bf16 v[126:129], v[150:153], v[212:215], v[126:129]
	v_mfma_f32_16x16x32_bf16 v[62:65], v[158:161], v[212:215], v[62:65]
	s_setprio 0
	s_barrier
	s_add_i32 s10, s25, s6
	v_lshl_add_u64 v[198:199], v[198:199], 0, s[28:29]
	s_mov_b32 m0, s10
	ds_read_b128 v[162:165], v202 offset:49152
	ds_read_b128 v[166:169], v202 offset:50176
	ds_read_b128 v[170:173], v202 offset:51200
	ds_read_b128 v[174:177], v202 offset:52224
	ds_read_b128 v[190:193], v202 offset:53248
	ds_read_b128 v[194:197], v202 offset:54272
	ds_read_b128 v[204:207], v202 offset:55296
	ds_read_b128 v[212:215], v202 offset:56320
	global_load_lds_dwordx4 v[198:199], off
	v_lshl_add_u64 v[198:199], v[208:209], 0, s[28:29]
	s_add_i32 m0, s10, 0x2000
	s_add_i32 s10, s26, s6
	global_load_lds_dwordx4 v[198:199], off
	v_lshl_add_u64 v[198:199], v[210:211], 0, s[28:29]
	s_mov_b32 m0, s10
	s_nop 0
	global_load_lds_dwordx4 v[198:199], off
	v_lshl_add_u64 v[198:199], v[216:217], 0, s[28:29]
	s_add_i32 m0, s10, 0x2000
	s_nop 0
	global_load_lds_dwordx4 v[198:199], off
	v_lshl_add_u64 v[198:199], v[218:219], 0, s[28:29]
	s_mov_b32 m0, s18
	s_nop 0
	global_load_lds_dwordx4 v[198:199], off
	v_lshl_add_u64 v[198:199], v[220:221], 0, s[28:29]
	s_mov_b32 m0, s19
	s_nop 0
	global_load_lds_dwordx4 v[198:199], off
	s_waitcnt vmcnt(8)
	s_waitcnt lgkmcnt(0)
	s_barrier
	s_setprio 1
	v_mfma_f32_16x16x32_bf16 v[70:73], v[130:133], v[162:165], v[70:73]
	v_mfma_f32_16x16x32_bf16 v[14:17], v[138:141], v[162:165], v[14:17]
	v_mfma_f32_16x16x32_bf16 v[50:53], v[130:133], v[170:173], v[50:53]
	v_mfma_f32_16x16x32_bf16 v[6:9], v[138:141], v[170:173], v[6:9]
	v_mfma_f32_16x16x32_bf16 v[106:109], v[130:133], v[190:193], v[106:109]
	v_mfma_f32_16x16x32_bf16 v[34:37], v[138:141], v[190:193], v[34:37]
	v_mfma_f32_16x16x32_bf16 v[102:105], v[130:133], v[204:207], v[102:105]
	v_mfma_f32_16x16x32_bf16 v[74:77], v[138:141], v[204:207], v[74:77]
	v_mfma_f32_16x16x32_bf16 v[70:73], v[134:137], v[166:169], v[70:73]
	v_mfma_f32_16x16x32_bf16 v[14:17], v[142:145], v[166:169], v[14:17]
	v_mfma_f32_16x16x32_bf16 v[50:53], v[134:137], v[174:177], v[50:53]
	v_mfma_f32_16x16x32_bf16 v[6:9], v[142:145], v[174:177], v[6:9]
	v_mfma_f32_16x16x32_bf16 v[106:109], v[134:137], v[194:197], v[106:109]
	v_mfma_f32_16x16x32_bf16 v[34:37], v[142:145], v[194:197], v[34:37]
	v_mfma_f32_16x16x32_bf16 v[102:105], v[134:137], v[212:215], v[102:105]
	v_mfma_f32_16x16x32_bf16 v[74:77], v[142:145], v[212:215], v[74:77]
	s_setprio 0
	s_setprio 1
	v_mfma_f32_16x16x32_bf16 v[66:69], v[146:149], v[162:165], v[66:69]
	v_mfma_f32_16x16x32_bf16 v[10:13], v[154:157], v[162:165], v[10:13]
	v_mfma_f32_16x16x32_bf16 v[46:49], v[146:149], v[170:173], v[46:49]
	v_mfma_f32_16x16x32_bf16 v[2:5], v[154:157], v[170:173], v[2:5]
	v_mfma_f32_16x16x32_bf16 v[110:113], v[146:149], v[190:193], v[110:113]
	v_mfma_f32_16x16x32_bf16 v[38:41], v[154:157], v[190:193], v[38:41]
	v_mfma_f32_16x16x32_bf16 v[98:101], v[146:149], v[204:207], v[98:101]
	v_mfma_f32_16x16x32_bf16 v[86:89], v[154:157], v[204:207], v[86:89]
	v_mfma_f32_16x16x32_bf16 v[66:69], v[150:153], v[166:169], v[66:69]
	v_mfma_f32_16x16x32_bf16 v[10:13], v[158:161], v[166:169], v[10:13]
	v_mfma_f32_16x16x32_bf16 v[46:49], v[150:153], v[174:177], v[46:49]
	v_mfma_f32_16x16x32_bf16 v[2:5], v[158:161], v[174:177], v[2:5]
	v_mfma_f32_16x16x32_bf16 v[110:113], v[150:153], v[194:197], v[110:113]
	v_mfma_f32_16x16x32_bf16 v[38:41], v[158:161], v[194:197], v[38:41]
	v_mfma_f32_16x16x32_bf16 v[98:101], v[150:153], v[212:215], v[98:101]
	v_mfma_f32_16x16x32_bf16 v[86:89], v[158:161], v[212:215], v[86:89]
	s_setprio 0
	s_barrier
	s_add_u32 s12, s12, 0x100
	s_addc_u32 s13, s13, 0
	s_add_u32 s0, s0, 0x100
	s_addc_u32 s1, s1, 0
	s_cmp_ge_i32 s24, s8
	s_mov_b32 s10, s24
	s_cbranch_scc0 .LBB0_931

.LBB0_1062:
	s_add_i32 s25, s12, 2
	s_add_u32 s33, s10, 0x80
	s_addc_u32 s13, s11, 0
	s_add_i32 s36, 0, 0x10000
	s_cmp_eq_u32 s20, s12
	s_cselect_b32 s13, s45, s13
	s_cselect_b32 s12, s44, s33
	v_add_u32_e32 v146, s36, v149
	s_cselect_b32 s35, s61, s24
	s_cselect_b32 s34, s60, s1
	s_add_i32 s33, 0, 0x14000
	ds_read_b128 v[142:145], v146
	ds_read_b128 v[152:155], v146 offset:1024
	ds_read_b128 v[156:159], v146 offset:2048
	ds_read_b128 v[160:163], v146 offset:3072
	v_add_u32_e32 v146, s33, v149
	ds_read_b128 v[164:167], v146
	ds_read_b128 v[168:171], v146 offset:1024
	ds_read_b128 v[172:175], v146 offset:2048
	ds_read_b128 v[176:179], v146 offset:3072
	v_lshl_add_u64 v[146:147], s[10:11], 0, v[138:139]
	s_add_i32 m0, s5, 0xc000
	ds_read_b128 v[180:183], v150
	ds_read_b128 v[184:187], v150 offset:1024
	ds_read_b128 v[188:191], v150 offset:2048
	ds_read_b128 v[192:195], v150 offset:3072
	ds_read_b128 v[196:199], v150 offset:4096
	ds_read_b128 v[200:203], v150 offset:5120
	ds_read_b128 v[204:207], v150 offset:6144
	ds_read_b128 v[212:215], v150 offset:7168
	global_load_lds_dwordx4 v[146:147], off
	v_lshl_add_u64 v[146:147], s[10:11], 0, v[140:141]
	s_add_i32 m0, s5, 0xe000
	s_nop 0
	global_load_lds_dwordx4 v[146:147], off
	s_waitcnt vmcnt(8)
	s_waitcnt lgkmcnt(0)
	s_barrier
	s_setprio 1
	v_mfma_f32_16x16x32_bf16 v[126:129], v[142:145], v[180:183], v[126:129]
	v_mfma_f32_16x16x32_bf16 v[122:125], v[156:159], v[180:183], v[122:125]
	v_mfma_f32_16x16x32_bf16 v[110:113], v[142:145], v[188:191], v[110:113]
	v_mfma_f32_16x16x32_bf16 v[106:109], v[156:159], v[188:191], v[106:109]
	v_mfma_f32_16x16x32_bf16 v[94:97], v[142:145], v[196:199], v[94:97]
	v_mfma_f32_16x16x32_bf16 v[90:93], v[156:159], v[196:199], v[90:93]
	v_mfma_f32_16x16x32_bf16 v[78:81], v[142:145], v[204:207], v[78:81]
	v_mfma_f32_16x16x32_bf16 v[74:77], v[156:159], v[204:207], v[74:77]
	v_mfma_f32_16x16x32_bf16 v[126:129], v[152:155], v[184:187], v[126:129]
	v_mfma_f32_16x16x32_bf16 v[122:125], v[160:163], v[184:187], v[122:125]
	v_mfma_f32_16x16x32_bf16 v[110:113], v[152:155], v[192:195], v[110:113]
	v_mfma_f32_16x16x32_bf16 v[106:109], v[160:163], v[192:195], v[106:109]
	v_mfma_f32_16x16x32_bf16 v[94:97], v[152:155], v[200:203], v[94:97]
	v_mfma_f32_16x16x32_bf16 v[90:93], v[160:163], v[200:203], v[90:93]
	v_mfma_f32_16x16x32_bf16 v[78:81], v[152:155], v[212:215], v[78:81]
	v_mfma_f32_16x16x32_bf16 v[74:77], v[160:163], v[212:215], v[74:77]
	s_setprio 0
	s_setprio 1
	v_mfma_f32_16x16x32_bf16 v[118:121], v[164:167], v[180:183], v[118:121]
	v_mfma_f32_16x16x32_bf16 v[114:117], v[172:175], v[180:183], v[114:117]
	v_mfma_f32_16x16x32_bf16 v[102:105], v[164:167], v[188:191], v[102:105]
	v_mfma_f32_16x16x32_bf16 v[98:101], v[172:175], v[188:191], v[98:101]
	v_mfma_f32_16x16x32_bf16 v[86:89], v[164:167], v[196:199], v[86:89]
	v_mfma_f32_16x16x32_bf16 v[82:85], v[172:175], v[196:199], v[82:85]
	v_mfma_f32_16x16x32_bf16 v[70:73], v[164:167], v[204:207], v[70:73]
	v_mfma_f32_16x16x32_bf16 v[66:69], v[172:175], v[204:207], v[66:69]
	v_mfma_f32_16x16x32_bf16 v[118:121], v[168:171], v[184:187], v[118:121]
	v_mfma_f32_16x16x32_bf16 v[114:117], v[176:179], v[184:187], v[114:117]
	v_mfma_f32_16x16x32_bf16 v[102:105], v[168:171], v[192:195], v[102:105]
	v_mfma_f32_16x16x32_bf16 v[98:101], v[176:179], v[192:195], v[98:101]
	v_mfma_f32_16x16x32_bf16 v[86:89], v[168:171], v[200:203], v[86:89]
	v_mfma_f32_16x16x32_bf16 v[82:85], v[176:179], v[200:203], v[82:85]
	v_mfma_f32_16x16x32_bf16 v[70:73], v[168:171], v[212:215], v[70:73]
	v_mfma_f32_16x16x32_bf16 v[66:69], v[176:179], v[212:215], v[66:69]
	s_setprio 0
	s_barrier
	s_add_i32 s36, s36, s4
	v_lshl_add_u64 v[146:147], s[34:35], 0, v[136:137]
	s_mov_b32 m0, s36
	ds_read_b128 v[180:183], v150 offset:16384
	ds_read_b128 v[184:187], v150 offset:17408
	ds_read_b128 v[188:191], v150 offset:18432
	ds_read_b128 v[192:195], v150 offset:19456
	ds_read_b128 v[196:199], v150 offset:20480
	ds_read_b128 v[200:203], v150 offset:21504
	ds_read_b128 v[204:207], v150 offset:22528
	ds_read_b128 v[212:215], v150 offset:23552
	global_load_lds_dwordx4 v[146:147], off
	s_add_i32 m0, s36, 0x2000
	v_lshl_add_u64 v[208:209], s[34:35], 0, v[132:133]
	s_add_u32 s34, s34, s46
	s_addc_u32 s35, s35, s47
	s_add_i32 s33, s33, s4
	global_load_lds_dwordx4 v[208:209], off
	v_lshl_add_u64 v[210:211], s[34:35], 0, v[136:137]
	s_mov_b32 m0, s33
	v_lshl_add_u64 v[216:217], s[34:35], 0, v[132:133]
	global_load_lds_dwordx4 v[210:211], off
	s_add_i32 m0, s33, 0x2000
	v_lshl_add_u64 v[218:219], s[12:13], 0, v[134:135]
	global_load_lds_dwordx4 v[216:217], off
	s_mov_b32 m0, s5
	v_lshl_add_u64 v[220:221], s[12:13], 0, v[130:131]
	global_load_lds_dwordx4 v[218:219], off
	s_mov_b32 m0, s6
	s_nop 0
	global_load_lds_dwordx4 v[220:221], off
	s_waitcnt vmcnt(8)
	s_waitcnt lgkmcnt(0)
	s_barrier
	s_setprio 1
	v_mfma_f32_16x16x32_bf16 v[62:65], v[142:145], v[180:183], v[62:65]
	v_mfma_f32_16x16x32_bf16 v[58:61], v[156:159], v[180:183], v[58:61]
	v_mfma_f32_16x16x32_bf16 v[46:49], v[142:145], v[188:191], v[46:49]
	v_mfma_f32_16x16x32_bf16 v[42:45], v[156:159], v[188:191], v[42:45]
	v_mfma_f32_16x16x32_bf16 v[30:33], v[142:145], v[196:199], v[30:33]
	v_mfma_f32_16x16x32_bf16 v[26:29], v[156:159], v[196:199], v[26:29]
	v_mfma_f32_16x16x32_bf16 v[14:17], v[142:145], v[204:207], v[14:17]
	v_mfma_f32_16x16x32_bf16 v[10:13], v[156:159], v[204:207], v[10:13]
	v_mfma_f32_16x16x32_bf16 v[62:65], v[152:155], v[184:187], v[62:65]
	v_mfma_f32_16x16x32_bf16 v[58:61], v[160:163], v[184:187], v[58:61]
	v_mfma_f32_16x16x32_bf16 v[46:49], v[152:155], v[192:195], v[46:49]
	v_mfma_f32_16x16x32_bf16 v[42:45], v[160:163], v[192:195], v[42:45]
	v_mfma_f32_16x16x32_bf16 v[30:33], v[152:155], v[200:203], v[30:33]
	v_mfma_f32_16x16x32_bf16 v[26:29], v[160:163], v[200:203], v[26:29]
	v_mfma_f32_16x16x32_bf16 v[14:17], v[152:155], v[212:215], v[14:17]
	v_mfma_f32_16x16x32_bf16 v[10:13], v[160:163], v[212:215], v[10:13]
	s_setprio 0
	s_setprio 1
	v_mfma_f32_16x16x32_bf16 v[54:57], v[164:167], v[180:183], v[54:57]
	v_mfma_f32_16x16x32_bf16 v[50:53], v[172:175], v[180:183], v[50:53]
	v_mfma_f32_16x16x32_bf16 v[38:41], v[164:167], v[188:191], v[38:41]
	v_mfma_f32_16x16x32_bf16 v[34:37], v[172:175], v[188:191], v[34:37]
	v_mfma_f32_16x16x32_bf16 v[22:25], v[164:167], v[196:199], v[22:25]
	v_mfma_f32_16x16x32_bf16 v[18:21], v[172:175], v[196:199], v[18:21]
	v_mfma_f32_16x16x32_bf16 v[6:9], v[164:167], v[204:207], v[6:9]
	v_mfma_f32_16x16x32_bf16 v[2:5], v[172:175], v[204:207], v[2:5]
	v_mfma_f32_16x16x32_bf16 v[54:57], v[168:171], v[184:187], v[54:57]
	v_mfma_f32_16x16x32_bf16 v[50:53], v[176:179], v[184:187], v[50:53]
	v_mfma_f32_16x16x32_bf16 v[38:41], v[168:171], v[192:195], v[38:41]
	v_mfma_f32_16x16x32_bf16 v[34:37], v[176:179], v[192:195], v[34:37]
	v_mfma_f32_16x16x32_bf16 v[22:25], v[168:171], v[200:203], v[22:25]
	v_mfma_f32_16x16x32_bf16 v[18:21], v[176:179], v[200:203], v[18:21]
	v_mfma_f32_16x16x32_bf16 v[6:9], v[168:171], v[212:215], v[6:9]
	v_mfma_f32_16x16x32_bf16 v[2:5], v[176:179], v[212:215], v[2:5]
	s_setprio 0
	s_barrier
	s_add_i32 s33, 0, 0x18000
	v_add_u32_e32 v151, s33, v149
	s_add_i32 s34, 0, 0x1c000
	ds_read_b128 v[142:145], v151
	ds_read_b128 v[152:155], v151 offset:1024
	ds_read_b128 v[156:159], v151 offset:2048
	ds_read_b128 v[160:163], v151 offset:3072
	v_add_u32_e32 v151, s34, v149
	ds_read_b128 v[164:167], v151
	ds_read_b128 v[168:171], v151 offset:1024
	ds_read_b128 v[172:175], v151 offset:2048
	ds_read_b128 v[176:179], v151 offset:3072
	s_add_u32 s12, s12, s46
	s_addc_u32 s13, s13, s47
	s_mov_b32 m0, s7
	v_lshl_add_u64 v[222:223], s[12:13], 0, v[134:135]
	ds_read_b128 v[180:183], v150 offset:32768
	ds_read_b128 v[184:187], v150 offset:33792
	ds_read_b128 v[188:191], v150 offset:34816
	ds_read_b128 v[192:195], v150 offset:35840
	ds_read_b128 v[196:199], v150 offset:36864
	ds_read_b128 v[200:203], v150 offset:37888
	ds_read_b128 v[204:207], v150 offset:38912
	ds_read_b128 v[212:215], v150 offset:39936
	global_load_lds_dwordx4 v[222:223], off
	v_lshl_add_u64 v[222:223], s[12:13], 0, v[130:131]
	s_mov_b32 m0, s8
	s_nop 0
	global_load_lds_dwordx4 v[222:223], off
	s_waitcnt vmcnt(8)
	s_waitcnt lgkmcnt(0)
	s_barrier
	s_setprio 1
	v_mfma_f32_16x16x32_bf16 v[126:129], v[142:145], v[180:183], v[126:129]
	v_mfma_f32_16x16x32_bf16 v[122:125], v[156:159], v[180:183], v[122:125]
	v_mfma_f32_16x16x32_bf16 v[110:113], v[142:145], v[188:191], v[110:113]
	v_mfma_f32_16x16x32_bf16 v[106:109], v[156:159], v[188:191], v[106:109]
	v_mfma_f32_16x16x32_bf16 v[94:97], v[142:145], v[196:199], v[94:97]
	v_mfma_f32_16x16x32_bf16 v[90:93], v[156:159], v[196:199], v[90:93]
	v_mfma_f32_16x16x32_bf16 v[78:81], v[142:145], v[204:207], v[78:81]
	v_mfma_f32_16x16x32_bf16 v[74:77], v[156:159], v[204:207], v[74:77]
	v_mfma_f32_16x16x32_bf16 v[126:129], v[152:155], v[184:187], v[126:129]
	v_mfma_f32_16x16x32_bf16 v[122:125], v[160:163], v[184:187], v[122:125]
	v_mfma_f32_16x16x32_bf16 v[110:113], v[152:155], v[192:195], v[110:113]
	v_mfma_f32_16x16x32_bf16 v[106:109], v[160:163], v[192:195], v[106:109]
	v_mfma_f32_16x16x32_bf16 v[94:97], v[152:155], v[200:203], v[94:97]
	v_mfma_f32_16x16x32_bf16 v[90:93], v[160:163], v[200:203], v[90:93]
	v_mfma_f32_16x16x32_bf16 v[78:81], v[152:155], v[212:215], v[78:81]
	v_mfma_f32_16x16x32_bf16 v[74:77], v[160:163], v[212:215], v[74:77]
	s_setprio 0
	s_setprio 1
	v_mfma_f32_16x16x32_bf16 v[118:121], v[164:167], v[180:183], v[118:121]
	v_mfma_f32_16x16x32_bf16 v[114:117], v[172:175], v[180:183], v[114:117]
	v_mfma_f32_16x16x32_bf16 v[102:105], v[164:167], v[188:191], v[102:105]
	v_mfma_f32_16x16x32_bf16 v[98:101], v[172:175], v[188:191], v[98:101]
	v_mfma_f32_16x16x32_bf16 v[86:89], v[164:167], v[196:199], v[86:89]
	v_mfma_f32_16x16x32_bf16 v[82:85], v[172:175], v[196:199], v[82:85]
	v_mfma_f32_16x16x32_bf16 v[70:73], v[164:167], v[204:207], v[70:73]
	v_mfma_f32_16x16x32_bf16 v[66:69], v[172:175], v[204:207], v[66:69]
	v_mfma_f32_16x16x32_bf16 v[118:121], v[168:171], v[184:187], v[118:121]
	v_mfma_f32_16x16x32_bf16 v[114:117], v[176:179], v[184:187], v[114:117]
	v_mfma_f32_16x16x32_bf16 v[102:105], v[168:171], v[192:195], v[102:105]
	v_mfma_f32_16x16x32_bf16 v[98:101], v[176:179], v[192:195], v[98:101]
	v_mfma_f32_16x16x32_bf16 v[86:89], v[168:171], v[200:203], v[86:89]
	v_mfma_f32_16x16x32_bf16 v[82:85], v[176:179], v[200:203], v[82:85]
	v_mfma_f32_16x16x32_bf16 v[70:73], v[168:171], v[212:215], v[70:73]
	v_mfma_f32_16x16x32_bf16 v[66:69], v[176:179], v[212:215], v[66:69]
	s_setprio 0
	s_barrier
	s_add_i32 s12, s33, s4
	v_lshl_add_u64 v[146:147], v[146:147], 0, s[28:29]
	s_mov_b32 m0, s12
	ds_read_b128 v[180:183], v150 offset:49152
	ds_read_b128 v[184:187], v150 offset:50176
	ds_read_b128 v[188:191], v150 offset:51200
	ds_read_b128 v[192:195], v150 offset:52224
	ds_read_b128 v[196:199], v150 offset:53248
	ds_read_b128 v[200:203], v150 offset:54272
	ds_read_b128 v[204:207], v150 offset:55296
	ds_read_b128 v[212:215], v150 offset:56320
	global_load_lds_dwordx4 v[146:147], off
	v_lshl_add_u64 v[146:147], v[208:209], 0, s[28:29]
	s_add_i32 m0, s12, 0x2000
	s_add_i32 s12, s34, s4
	global_load_lds_dwordx4 v[146:147], off
	v_lshl_add_u64 v[146:147], v[210:211], 0, s[28:29]
	s_mov_b32 m0, s12
	s_nop 0
	global_load_lds_dwordx4 v[146:147], off
	v_lshl_add_u64 v[146:147], v[216:217], 0, s[28:29]
	s_add_i32 m0, s12, 0x2000
	s_nop 0
	global_load_lds_dwordx4 v[146:147], off
	v_lshl_add_u64 v[146:147], v[218:219], 0, s[28:29]
	s_mov_b32 m0, s9
	s_nop 0
	global_load_lds_dwordx4 v[146:147], off
	v_lshl_add_u64 v[146:147], v[220:221], 0, s[28:29]
	s_mov_b32 m0, s14
	s_nop 0
	global_load_lds_dwordx4 v[146:147], off
	s_waitcnt vmcnt(8)
	s_waitcnt lgkmcnt(0)
	s_barrier
	s_setprio 1
	v_mfma_f32_16x16x32_bf16 v[62:65], v[142:145], v[180:183], v[62:65]
	v_mfma_f32_16x16x32_bf16 v[58:61], v[156:159], v[180:183], v[58:61]
	v_mfma_f32_16x16x32_bf16 v[46:49], v[142:145], v[188:191], v[46:49]
	v_mfma_f32_16x16x32_bf16 v[42:45], v[156:159], v[188:191], v[42:45]
	v_mfma_f32_16x16x32_bf16 v[30:33], v[142:145], v[196:199], v[30:33]
	v_mfma_f32_16x16x32_bf16 v[26:29], v[156:159], v[196:199], v[26:29]
	v_mfma_f32_16x16x32_bf16 v[14:17], v[142:145], v[204:207], v[14:17]
	v_mfma_f32_16x16x32_bf16 v[10:13], v[156:159], v[204:207], v[10:13]
	v_mfma_f32_16x16x32_bf16 v[62:65], v[152:155], v[184:187], v[62:65]
	v_mfma_f32_16x16x32_bf16 v[58:61], v[160:163], v[184:187], v[58:61]
	v_mfma_f32_16x16x32_bf16 v[46:49], v[152:155], v[192:195], v[46:49]
	v_mfma_f32_16x16x32_bf16 v[42:45], v[160:163], v[192:195], v[42:45]
	v_mfma_f32_16x16x32_bf16 v[30:33], v[152:155], v[200:203], v[30:33]
	v_mfma_f32_16x16x32_bf16 v[26:29], v[160:163], v[200:203], v[26:29]
	v_mfma_f32_16x16x32_bf16 v[14:17], v[152:155], v[212:215], v[14:17]
	v_mfma_f32_16x16x32_bf16 v[10:13], v[160:163], v[212:215], v[10:13]
	s_setprio 0
	s_setprio 1
	v_mfma_f32_16x16x32_bf16 v[54:57], v[164:167], v[180:183], v[54:57]
	v_mfma_f32_16x16x32_bf16 v[50:53], v[172:175], v[180:183], v[50:53]
	v_mfma_f32_16x16x32_bf16 v[38:41], v[164:167], v[188:191], v[38:41]
	v_mfma_f32_16x16x32_bf16 v[34:37], v[172:175], v[188:191], v[34:37]
	v_mfma_f32_16x16x32_bf16 v[22:25], v[164:167], v[196:199], v[22:25]
	v_mfma_f32_16x16x32_bf16 v[18:21], v[172:175], v[196:199], v[18:21]
	v_mfma_f32_16x16x32_bf16 v[6:9], v[164:167], v[204:207], v[6:9]
	v_mfma_f32_16x16x32_bf16 v[2:5], v[172:175], v[204:207], v[2:5]
	v_mfma_f32_16x16x32_bf16 v[54:57], v[168:171], v[184:187], v[54:57]
	v_mfma_f32_16x16x32_bf16 v[50:53], v[176:179], v[184:187], v[50:53]
	v_mfma_f32_16x16x32_bf16 v[38:41], v[168:171], v[192:195], v[38:41]
	v_mfma_f32_16x16x32_bf16 v[34:37], v[176:179], v[192:195], v[34:37]
	v_mfma_f32_16x16x32_bf16 v[22:25], v[168:171], v[200:203], v[22:25]
	v_mfma_f32_16x16x32_bf16 v[18:21], v[176:179], v[200:203], v[18:21]
	v_mfma_f32_16x16x32_bf16 v[6:9], v[168:171], v[212:215], v[6:9]
	v_mfma_f32_16x16x32_bf16 v[2:5], v[176:179], v[212:215], v[2:5]
	s_setprio 0
	s_barrier
	s_add_u32 s1, s1, 0x100
	s_addc_u32 s24, s24, 0
	s_add_u32 s10, s10, 0x100
	s_addc_u32 s11, s11, 0
	s_cmp_ge_i32 s25, s18
	s_mov_b32 s12, s25
	s_cbranch_scc0 .LBB0_1062

.LBB0_1103:
	s_add_i32 s47, s36, 2
	s_add_u32 s48, s44, 0x80
	s_addc_u32 s49, s45, 0
	s_add_i32 s52, 0, 0x10000
	s_cmp_eq_u32 s19, s36
	s_cselect_b32 s49, s39, s49
	s_cselect_b32 s48, s38, s48
	v_add_u32_e32 v145, s52, v143
	s_cselect_b32 s51, s41, s35
	s_cselect_b32 s50, s40, s34
	s_add_i32 s36, 0, 0x14000
	ds_read_b128 v[146:149], v145
	ds_read_b128 v[150:153], v145 offset:1024
	ds_read_b128 v[154:157], v145 offset:2048
	ds_read_b128 v[158:161], v145 offset:3072
	v_add_u32_e32 v145, s36, v143
	ds_read_b128 v[162:165], v145
	ds_read_b128 v[166:169], v145 offset:1024
	ds_read_b128 v[170:173], v145 offset:2048
	ds_read_b128 v[174:177], v145 offset:3072
	v_lshl_add_u64 v[210:211], s[44:45], 0, v[138:139]
	s_add_i32 m0, s5, 0xc000
	ds_read_b128 v[178:181], v144
	ds_read_b128 v[182:185], v144 offset:1024
	ds_read_b128 v[186:189], v144 offset:2048
	ds_read_b128 v[190:193], v144 offset:3072
	ds_read_b128 v[194:197], v144 offset:4096
	ds_read_b128 v[198:201], v144 offset:5120
	ds_read_b128 v[202:205], v144 offset:6144
	ds_read_b128 v[206:209], v144 offset:7168
	global_load_lds_dwordx4 v[210:211], off
	v_lshl_add_u64 v[210:211], s[44:45], 0, v[140:141]
	s_add_i32 m0, s5, 0xe000
	s_nop 0
	global_load_lds_dwordx4 v[210:211], off
	s_waitcnt vmcnt(8)
	s_waitcnt lgkmcnt(0)
	s_barrier
	s_setprio 1
	v_mfma_f32_16x16x32_bf16 v[122:125], v[146:149], v[178:181], v[122:125]
	v_mfma_f32_16x16x32_bf16 v[126:129], v[154:157], v[178:181], v[126:129]
	v_mfma_f32_16x16x32_bf16 v[110:113], v[146:149], v[186:189], v[110:113]
	v_mfma_f32_16x16x32_bf16 v[106:109], v[154:157], v[186:189], v[106:109]
	v_mfma_f32_16x16x32_bf16 v[94:97], v[146:149], v[194:197], v[94:97]
	v_mfma_f32_16x16x32_bf16 v[90:93], v[154:157], v[194:197], v[90:93]
	v_mfma_f32_16x16x32_bf16 v[78:81], v[146:149], v[202:205], v[78:81]
	v_mfma_f32_16x16x32_bf16 v[74:77], v[154:157], v[202:205], v[74:77]
	v_mfma_f32_16x16x32_bf16 v[122:125], v[150:153], v[182:185], v[122:125]
	v_mfma_f32_16x16x32_bf16 v[126:129], v[158:161], v[182:185], v[126:129]
	v_mfma_f32_16x16x32_bf16 v[110:113], v[150:153], v[190:193], v[110:113]
	v_mfma_f32_16x16x32_bf16 v[106:109], v[158:161], v[190:193], v[106:109]
	v_mfma_f32_16x16x32_bf16 v[94:97], v[150:153], v[198:201], v[94:97]
	v_mfma_f32_16x16x32_bf16 v[90:93], v[158:161], v[198:201], v[90:93]
	v_mfma_f32_16x16x32_bf16 v[78:81], v[150:153], v[206:209], v[78:81]
	v_mfma_f32_16x16x32_bf16 v[74:77], v[158:161], v[206:209], v[74:77]
	s_setprio 0
	s_setprio 1
	v_mfma_f32_16x16x32_bf16 v[118:121], v[162:165], v[178:181], v[118:121]
	v_mfma_f32_16x16x32_bf16 v[114:117], v[170:173], v[178:181], v[114:117]
	v_mfma_f32_16x16x32_bf16 v[102:105], v[162:165], v[186:189], v[102:105]
	v_mfma_f32_16x16x32_bf16 v[98:101], v[170:173], v[186:189], v[98:101]
	v_mfma_f32_16x16x32_bf16 v[86:89], v[162:165], v[194:197], v[86:89]
	v_mfma_f32_16x16x32_bf16 v[82:85], v[170:173], v[194:197], v[82:85]
	v_mfma_f32_16x16x32_bf16 v[70:73], v[162:165], v[202:205], v[70:73]
	v_mfma_f32_16x16x32_bf16 v[66:69], v[170:173], v[202:205], v[66:69]
	v_mfma_f32_16x16x32_bf16 v[118:121], v[166:169], v[182:185], v[118:121]
	v_mfma_f32_16x16x32_bf16 v[114:117], v[174:177], v[182:185], v[114:117]
	v_mfma_f32_16x16x32_bf16 v[102:105], v[166:169], v[190:193], v[102:105]
	v_mfma_f32_16x16x32_bf16 v[98:101], v[174:177], v[190:193], v[98:101]
	v_mfma_f32_16x16x32_bf16 v[86:89], v[166:169], v[198:201], v[86:89]
	v_mfma_f32_16x16x32_bf16 v[82:85], v[174:177], v[198:201], v[82:85]
	v_mfma_f32_16x16x32_bf16 v[70:73], v[166:169], v[206:209], v[70:73]
	v_mfma_f32_16x16x32_bf16 v[66:69], v[174:177], v[206:209], v[66:69]
	s_setprio 0
	s_barrier
	s_add_i32 s52, s52, s4
	v_lshl_add_u64 v[210:211], s[50:51], 0, v[136:137]
	s_mov_b32 m0, s52
	ds_read_b128 v[178:181], v144 offset:16384
	ds_read_b128 v[182:185], v144 offset:17408
	ds_read_b128 v[186:189], v144 offset:18432
	ds_read_b128 v[190:193], v144 offset:19456
	ds_read_b128 v[194:197], v144 offset:20480
	ds_read_b128 v[198:201], v144 offset:21504
	ds_read_b128 v[202:205], v144 offset:22528
	ds_read_b128 v[206:209], v144 offset:23552
	global_load_lds_dwordx4 v[210:211], off
	s_add_i32 m0, s52, 0x2000
	v_lshl_add_u64 v[212:213], s[50:51], 0, v[132:133]
	s_add_u32 s50, s50, s0
	s_addc_u32 s51, s51, s1
	s_add_i32 s36, s36, s4
	global_load_lds_dwordx4 v[212:213], off
	v_lshl_add_u64 v[214:215], s[50:51], 0, v[136:137]
	s_mov_b32 m0, s36
	v_lshl_add_u64 v[216:217], s[50:51], 0, v[132:133]
	global_load_lds_dwordx4 v[214:215], off
	s_add_i32 m0, s36, 0x2000
	v_lshl_add_u64 v[218:219], s[48:49], 0, v[134:135]
	global_load_lds_dwordx4 v[216:217], off
	s_mov_b32 m0, s5
	v_lshl_add_u64 v[220:221], s[48:49], 0, v[130:131]
	global_load_lds_dwordx4 v[218:219], off
	s_mov_b32 m0, s6
	s_nop 0
	global_load_lds_dwordx4 v[220:221], off
	s_waitcnt vmcnt(8)
	s_waitcnt lgkmcnt(0)
	s_barrier
	s_setprio 1
	v_mfma_f32_16x16x32_bf16 v[62:65], v[146:149], v[178:181], v[62:65]
	v_mfma_f32_16x16x32_bf16 v[58:61], v[154:157], v[178:181], v[58:61]
	v_mfma_f32_16x16x32_bf16 v[46:49], v[146:149], v[186:189], v[46:49]
	v_mfma_f32_16x16x32_bf16 v[42:45], v[154:157], v[186:189], v[42:45]
	v_mfma_f32_16x16x32_bf16 v[30:33], v[146:149], v[194:197], v[30:33]
	v_mfma_f32_16x16x32_bf16 v[26:29], v[154:157], v[194:197], v[26:29]
	v_mfma_f32_16x16x32_bf16 v[14:17], v[146:149], v[202:205], v[14:17]
	v_mfma_f32_16x16x32_bf16 v[10:13], v[154:157], v[202:205], v[10:13]
	v_mfma_f32_16x16x32_bf16 v[62:65], v[150:153], v[182:185], v[62:65]
	v_mfma_f32_16x16x32_bf16 v[58:61], v[158:161], v[182:185], v[58:61]
	v_mfma_f32_16x16x32_bf16 v[46:49], v[150:153], v[190:193], v[46:49]
	v_mfma_f32_16x16x32_bf16 v[42:45], v[158:161], v[190:193], v[42:45]
	v_mfma_f32_16x16x32_bf16 v[30:33], v[150:153], v[198:201], v[30:33]
	v_mfma_f32_16x16x32_bf16 v[26:29], v[158:161], v[198:201], v[26:29]
	v_mfma_f32_16x16x32_bf16 v[14:17], v[150:153], v[206:209], v[14:17]
	v_mfma_f32_16x16x32_bf16 v[10:13], v[158:161], v[206:209], v[10:13]
	s_setprio 0
	s_setprio 1
	v_mfma_f32_16x16x32_bf16 v[54:57], v[162:165], v[178:181], v[54:57]
	v_mfma_f32_16x16x32_bf16 v[50:53], v[170:173], v[178:181], v[50:53]
	v_mfma_f32_16x16x32_bf16 v[38:41], v[162:165], v[186:189], v[38:41]
	v_mfma_f32_16x16x32_bf16 v[34:37], v[170:173], v[186:189], v[34:37]
	v_mfma_f32_16x16x32_bf16 v[22:25], v[162:165], v[194:197], v[22:25]
	v_mfma_f32_16x16x32_bf16 v[18:21], v[170:173], v[194:197], v[18:21]
	v_mfma_f32_16x16x32_bf16 v[6:9], v[162:165], v[202:205], v[6:9]
	v_mfma_f32_16x16x32_bf16 v[2:5], v[170:173], v[202:205], v[2:5]
	v_mfma_f32_16x16x32_bf16 v[54:57], v[166:169], v[182:185], v[54:57]
	v_mfma_f32_16x16x32_bf16 v[50:53], v[174:177], v[182:185], v[50:53]
	v_mfma_f32_16x16x32_bf16 v[38:41], v[166:169], v[190:193], v[38:41]
	v_mfma_f32_16x16x32_bf16 v[34:37], v[174:177], v[190:193], v[34:37]
	v_mfma_f32_16x16x32_bf16 v[22:25], v[166:169], v[198:201], v[22:25]
	v_mfma_f32_16x16x32_bf16 v[18:21], v[174:177], v[198:201], v[18:21]
	v_mfma_f32_16x16x32_bf16 v[6:9], v[166:169], v[206:209], v[6:9]
	v_mfma_f32_16x16x32_bf16 v[2:5], v[174:177], v[206:209], v[2:5]
	s_setprio 0
	s_barrier
	s_add_i32 s36, 0, 0x18000
	v_add_u32_e32 v145, s36, v143
	s_add_i32 s50, 0, 0x1c000
	ds_read_b128 v[146:149], v145
	ds_read_b128 v[150:153], v145 offset:1024
	ds_read_b128 v[154:157], v145 offset:2048
	ds_read_b128 v[158:161], v145 offset:3072
	v_add_u32_e32 v145, s50, v143
	ds_read_b128 v[162:165], v145
	ds_read_b128 v[166:169], v145 offset:1024
	ds_read_b128 v[170:173], v145 offset:2048
	ds_read_b128 v[174:177], v145 offset:3072
	s_add_u32 s48, s48, s0
	s_addc_u32 s49, s49, s1
	s_mov_b32 m0, s7
	v_lshl_add_u64 v[222:223], s[48:49], 0, v[134:135]
	ds_read_b128 v[178:181], v144 offset:32768
	ds_read_b128 v[182:185], v144 offset:33792
	ds_read_b128 v[186:189], v144 offset:34816
	ds_read_b128 v[190:193], v144 offset:35840
	ds_read_b128 v[194:197], v144 offset:36864
	ds_read_b128 v[198:201], v144 offset:37888
	ds_read_b128 v[202:205], v144 offset:38912
	ds_read_b128 v[206:209], v144 offset:39936
	global_load_lds_dwordx4 v[222:223], off
	v_lshl_add_u64 v[222:223], s[48:49], 0, v[130:131]
	s_mov_b32 m0, s8
	s_nop 0
	global_load_lds_dwordx4 v[222:223], off
	s_waitcnt vmcnt(8)
	s_waitcnt lgkmcnt(0)
	s_barrier
	s_setprio 1
	v_mfma_f32_16x16x32_bf16 v[122:125], v[146:149], v[178:181], v[122:125]
	v_mfma_f32_16x16x32_bf16 v[126:129], v[154:157], v[178:181], v[126:129]
	v_mfma_f32_16x16x32_bf16 v[110:113], v[146:149], v[186:189], v[110:113]
	v_mfma_f32_16x16x32_bf16 v[106:109], v[154:157], v[186:189], v[106:109]
	v_mfma_f32_16x16x32_bf16 v[94:97], v[146:149], v[194:197], v[94:97]
	v_mfma_f32_16x16x32_bf16 v[90:93], v[154:157], v[194:197], v[90:93]
	v_mfma_f32_16x16x32_bf16 v[78:81], v[146:149], v[202:205], v[78:81]
	v_mfma_f32_16x16x32_bf16 v[74:77], v[154:157], v[202:205], v[74:77]
	v_mfma_f32_16x16x32_bf16 v[122:125], v[150:153], v[182:185], v[122:125]
	v_mfma_f32_16x16x32_bf16 v[126:129], v[158:161], v[182:185], v[126:129]
	v_mfma_f32_16x16x32_bf16 v[110:113], v[150:153], v[190:193], v[110:113]
	v_mfma_f32_16x16x32_bf16 v[106:109], v[158:161], v[190:193], v[106:109]
	v_mfma_f32_16x16x32_bf16 v[94:97], v[150:153], v[198:201], v[94:97]
	v_mfma_f32_16x16x32_bf16 v[90:93], v[158:161], v[198:201], v[90:93]
	v_mfma_f32_16x16x32_bf16 v[78:81], v[150:153], v[206:209], v[78:81]
	v_mfma_f32_16x16x32_bf16 v[74:77], v[158:161], v[206:209], v[74:77]
	s_setprio 0
	s_setprio 1
	v_mfma_f32_16x16x32_bf16 v[118:121], v[162:165], v[178:181], v[118:121]
	v_mfma_f32_16x16x32_bf16 v[114:117], v[170:173], v[178:181], v[114:117]
	v_mfma_f32_16x16x32_bf16 v[102:105], v[162:165], v[186:189], v[102:105]
	v_mfma_f32_16x16x32_bf16 v[98:101], v[170:173], v[186:189], v[98:101]
	v_mfma_f32_16x16x32_bf16 v[86:89], v[162:165], v[194:197], v[86:89]
	v_mfma_f32_16x16x32_bf16 v[82:85], v[170:173], v[194:197], v[82:85]
	v_mfma_f32_16x16x32_bf16 v[70:73], v[162:165], v[202:205], v[70:73]
	v_mfma_f32_16x16x32_bf16 v[66:69], v[170:173], v[202:205], v[66:69]
	v_mfma_f32_16x16x32_bf16 v[118:121], v[166:169], v[182:185], v[118:121]
	v_mfma_f32_16x16x32_bf16 v[114:117], v[174:177], v[182:185], v[114:117]
	v_mfma_f32_16x16x32_bf16 v[102:105], v[166:169], v[190:193], v[102:105]
	v_mfma_f32_16x16x32_bf16 v[98:101], v[174:177], v[190:193], v[98:101]
	v_mfma_f32_16x16x32_bf16 v[86:89], v[166:169], v[198:201], v[86:89]
	v_mfma_f32_16x16x32_bf16 v[82:85], v[174:177], v[198:201], v[82:85]
	v_mfma_f32_16x16x32_bf16 v[70:73], v[166:169], v[206:209], v[70:73]
	v_mfma_f32_16x16x32_bf16 v[66:69], v[174:177], v[206:209], v[66:69]
	s_setprio 0
	s_barrier
	s_add_i32 s36, s36, s4
	v_lshl_add_u64 v[210:211], v[210:211], 0, s[28:29]
	s_mov_b32 m0, s36
	ds_read_b128 v[178:181], v144 offset:49152
	ds_read_b128 v[182:185], v144 offset:50176
	ds_read_b128 v[186:189], v144 offset:51200
	ds_read_b128 v[190:193], v144 offset:52224
	ds_read_b128 v[194:197], v144 offset:53248
	ds_read_b128 v[198:201], v144 offset:54272
	ds_read_b128 v[202:205], v144 offset:55296
	ds_read_b128 v[206:209], v144 offset:56320
	global_load_lds_dwordx4 v[210:211], off
	v_lshl_add_u64 v[210:211], v[212:213], 0, s[28:29]
	s_add_i32 m0, s36, 0x2000
	s_add_i32 s36, s50, s4
	global_load_lds_dwordx4 v[210:211], off
	v_lshl_add_u64 v[210:211], v[214:215], 0, s[28:29]
	s_mov_b32 m0, s36
	s_nop 0
	global_load_lds_dwordx4 v[210:211], off
	v_lshl_add_u64 v[210:211], v[216:217], 0, s[28:29]
	s_add_i32 m0, s36, 0x2000
	s_nop 0
	global_load_lds_dwordx4 v[210:211], off
	v_lshl_add_u64 v[210:211], v[218:219], 0, s[28:29]
	s_mov_b32 m0, s9
	s_nop 0
	global_load_lds_dwordx4 v[210:211], off
	v_lshl_add_u64 v[210:211], v[220:221], 0, s[28:29]
	s_mov_b32 m0, s14
	s_nop 0
	global_load_lds_dwordx4 v[210:211], off
	s_waitcnt vmcnt(8)
	s_waitcnt lgkmcnt(0)
	s_barrier
	s_setprio 1
	v_mfma_f32_16x16x32_bf16 v[62:65], v[146:149], v[178:181], v[62:65]
	v_mfma_f32_16x16x32_bf16 v[58:61], v[154:157], v[178:181], v[58:61]
	v_mfma_f32_16x16x32_bf16 v[46:49], v[146:149], v[186:189], v[46:49]
	v_mfma_f32_16x16x32_bf16 v[42:45], v[154:157], v[186:189], v[42:45]
	v_mfma_f32_16x16x32_bf16 v[30:33], v[146:149], v[194:197], v[30:33]
	v_mfma_f32_16x16x32_bf16 v[26:29], v[154:157], v[194:197], v[26:29]
	v_mfma_f32_16x16x32_bf16 v[14:17], v[146:149], v[202:205], v[14:17]
	v_mfma_f32_16x16x32_bf16 v[10:13], v[154:157], v[202:205], v[10:13]
	v_mfma_f32_16x16x32_bf16 v[62:65], v[150:153], v[182:185], v[62:65]
	v_mfma_f32_16x16x32_bf16 v[58:61], v[158:161], v[182:185], v[58:61]
	v_mfma_f32_16x16x32_bf16 v[46:49], v[150:153], v[190:193], v[46:49]
	v_mfma_f32_16x16x32_bf16 v[42:45], v[158:161], v[190:193], v[42:45]
	v_mfma_f32_16x16x32_bf16 v[30:33], v[150:153], v[198:201], v[30:33]
	v_mfma_f32_16x16x32_bf16 v[26:29], v[158:161], v[198:201], v[26:29]
	v_mfma_f32_16x16x32_bf16 v[14:17], v[150:153], v[206:209], v[14:17]
	v_mfma_f32_16x16x32_bf16 v[10:13], v[158:161], v[206:209], v[10:13]
	s_setprio 0
	s_setprio 1
	v_mfma_f32_16x16x32_bf16 v[54:57], v[162:165], v[178:181], v[54:57]
	v_mfma_f32_16x16x32_bf16 v[50:53], v[170:173], v[178:181], v[50:53]
	v_mfma_f32_16x16x32_bf16 v[38:41], v[162:165], v[186:189], v[38:41]
	v_mfma_f32_16x16x32_bf16 v[34:37], v[170:173], v[186:189], v[34:37]
	v_mfma_f32_16x16x32_bf16 v[22:25], v[162:165], v[194:197], v[22:25]
	v_mfma_f32_16x16x32_bf16 v[18:21], v[170:173], v[194:197], v[18:21]
	v_mfma_f32_16x16x32_bf16 v[6:9], v[162:165], v[202:205], v[6:9]
	v_mfma_f32_16x16x32_bf16 v[2:5], v[170:173], v[202:205], v[2:5]
	v_mfma_f32_16x16x32_bf16 v[54:57], v[166:169], v[182:185], v[54:57]
	v_mfma_f32_16x16x32_bf16 v[50:53], v[174:177], v[182:185], v[50:53]
	v_mfma_f32_16x16x32_bf16 v[38:41], v[166:169], v[190:193], v[38:41]
	v_mfma_f32_16x16x32_bf16 v[34:37], v[174:177], v[190:193], v[34:37]
	v_mfma_f32_16x16x32_bf16 v[22:25], v[166:169], v[198:201], v[22:25]
	v_mfma_f32_16x16x32_bf16 v[18:21], v[174:177], v[198:201], v[18:21]
	v_mfma_f32_16x16x32_bf16 v[6:9], v[166:169], v[206:209], v[6:9]
	v_mfma_f32_16x16x32_bf16 v[2:5], v[174:177], v[206:209], v[2:5]
	s_setprio 0
	s_barrier
	s_add_u32 s44, s44, 0x100
	s_addc_u32 s45, s45, 0
	s_add_u32 s34, s34, 0x100
	s_addc_u32 s35, s35, 0
	s_cmp_ge_i32 s47, s15
	s_mov_b32 s36, s47
	s_cbranch_scc0 .LBB0_1103

.LBB0_1182:
	s_add_i32 s7, s6, 2
	s_add_u32 s8, s10, 0x80
	s_addc_u32 s9, s11, 0
	s_add_i32 s14, 0, 0x10000
	s_cmp_eq_u32 s85, s6
	s_cselect_b32 s13, s73, s9
	s_cselect_b32 s12, s72, s8
	s_cselect_b32 s9, s75, s5
	s_cselect_b32 s8, s74, s1
	s_add_i32 s6, 0, 0x14000
	v_add_u32_e32 v154, s14, v189
	v_add_u32_e32 v170, s6, v189
	ds_read_b128 v[130:133], v154
	ds_read_b128 v[134:137], v154 offset:1024
	ds_read_b128 v[150:153], v154 offset:2048
	ds_read_b128 v[154:157], v154 offset:3072
	ds_read_b128 v[158:161], v170
	ds_read_b128 v[162:165], v170 offset:1024
	ds_read_b128 v[166:169], v170 offset:2048
	ds_read_b128 v[170:173], v170 offset:3072
	v_lshl_add_u64 v[186:187], s[10:11], 0, v[146:147]
	s_add_i32 m0, s27, 0xc000
	ds_read_b128 v[174:177], v190
	ds_read_b128 v[178:181], v190 offset:1024
	ds_read_b128 v[182:185], v190 offset:2048
	ds_read_b128 v[192:195], v190 offset:3072
	ds_read_b128 v[196:199], v190 offset:4096
	ds_read_b128 v[200:203], v190 offset:5120
	ds_read_b128 v[204:207], v190 offset:6144
	ds_read_b128 v[212:215], v190 offset:7168
	global_load_lds_dwordx4 v[186:187], off
	v_lshl_add_u64 v[186:187], s[10:11], 0, v[148:149]
	s_add_i32 m0, s27, 0xe000
	s_nop 0
	global_load_lds_dwordx4 v[186:187], off
	s_waitcnt vmcnt(8)
	s_waitcnt lgkmcnt(0)
	s_barrier
	s_setprio 1
	v_mfma_f32_16x16x32_bf16 v[126:129], v[130:133], v[174:177], v[126:129]
	v_mfma_f32_16x16x32_bf16 v[122:125], v[150:153], v[174:177], v[122:125]
	v_mfma_f32_16x16x32_bf16 v[110:113], v[130:133], v[182:185], v[110:113]
	v_mfma_f32_16x16x32_bf16 v[106:109], v[150:153], v[182:185], v[106:109]
	v_mfma_f32_16x16x32_bf16 v[94:97], v[130:133], v[196:199], v[94:97]
	v_mfma_f32_16x16x32_bf16 v[90:93], v[150:153], v[196:199], v[90:93]
	v_mfma_f32_16x16x32_bf16 v[78:81], v[130:133], v[204:207], v[78:81]
	v_mfma_f32_16x16x32_bf16 v[74:77], v[150:153], v[204:207], v[74:77]
	v_mfma_f32_16x16x32_bf16 v[126:129], v[134:137], v[178:181], v[126:129]
	v_mfma_f32_16x16x32_bf16 v[122:125], v[154:157], v[178:181], v[122:125]
	v_mfma_f32_16x16x32_bf16 v[110:113], v[134:137], v[192:195], v[110:113]
	v_mfma_f32_16x16x32_bf16 v[106:109], v[154:157], v[192:195], v[106:109]
	v_mfma_f32_16x16x32_bf16 v[94:97], v[134:137], v[200:203], v[94:97]
	v_mfma_f32_16x16x32_bf16 v[90:93], v[154:157], v[200:203], v[90:93]
	v_mfma_f32_16x16x32_bf16 v[78:81], v[134:137], v[212:215], v[78:81]
	v_mfma_f32_16x16x32_bf16 v[74:77], v[154:157], v[212:215], v[74:77]
	s_setprio 0
	s_setprio 1
	v_mfma_f32_16x16x32_bf16 v[118:121], v[158:161], v[174:177], v[118:121]
	v_mfma_f32_16x16x32_bf16 v[114:117], v[166:169], v[174:177], v[114:117]
	v_mfma_f32_16x16x32_bf16 v[102:105], v[158:161], v[182:185], v[102:105]
	v_mfma_f32_16x16x32_bf16 v[98:101], v[166:169], v[182:185], v[98:101]
	v_mfma_f32_16x16x32_bf16 v[86:89], v[158:161], v[196:199], v[86:89]
	v_mfma_f32_16x16x32_bf16 v[82:85], v[166:169], v[196:199], v[82:85]
	v_mfma_f32_16x16x32_bf16 v[70:73], v[158:161], v[204:207], v[70:73]
	v_mfma_f32_16x16x32_bf16 v[66:69], v[166:169], v[204:207], v[66:69]
	v_mfma_f32_16x16x32_bf16 v[118:121], v[162:165], v[178:181], v[118:121]
	v_mfma_f32_16x16x32_bf16 v[114:117], v[170:173], v[178:181], v[114:117]
	v_mfma_f32_16x16x32_bf16 v[102:105], v[162:165], v[192:195], v[102:105]
	v_mfma_f32_16x16x32_bf16 v[98:101], v[170:173], v[192:195], v[98:101]
	v_mfma_f32_16x16x32_bf16 v[86:89], v[162:165], v[200:203], v[86:89]
	v_mfma_f32_16x16x32_bf16 v[82:85], v[170:173], v[200:203], v[82:85]
	v_mfma_f32_16x16x32_bf16 v[70:73], v[162:165], v[212:215], v[70:73]
	v_mfma_f32_16x16x32_bf16 v[66:69], v[170:173], v[212:215], v[66:69]
	s_setprio 0
	s_barrier
	s_add_i32 s14, s14, s26
	v_lshl_add_u64 v[186:187], s[8:9], 0, v[144:145]
	s_mov_b32 m0, s14
	ds_read_b128 v[174:177], v190 offset:16384
	ds_read_b128 v[178:181], v190 offset:17408
	ds_read_b128 v[182:185], v190 offset:18432
	ds_read_b128 v[192:195], v190 offset:19456
	ds_read_b128 v[196:199], v190 offset:20480
	ds_read_b128 v[200:203], v190 offset:21504
	ds_read_b128 v[204:207], v190 offset:22528
	ds_read_b128 v[212:215], v190 offset:23552
	global_load_lds_dwordx4 v[186:187], off
	s_add_i32 m0, s14, 0x2000
	v_lshl_add_u64 v[208:209], s[8:9], 0, v[140:141]
	s_add_u32 s8, s8, s56
	s_addc_u32 s9, s9, s57
	s_add_i32 s6, s6, s26
	global_load_lds_dwordx4 v[208:209], off
	v_lshl_add_u64 v[210:211], s[8:9], 0, v[144:145]
	s_mov_b32 m0, s6
	v_lshl_add_u64 v[216:217], s[8:9], 0, v[140:141]
	global_load_lds_dwordx4 v[210:211], off
	s_add_i32 m0, s6, 0x2000
	v_lshl_add_u64 v[218:219], s[12:13], 0, v[142:143]
	global_load_lds_dwordx4 v[216:217], off
	s_mov_b32 m0, s27
	v_lshl_add_u64 v[220:221], s[12:13], 0, v[138:139]
	global_load_lds_dwordx4 v[218:219], off
	s_mov_b32 m0, s38
	s_nop 0
	global_load_lds_dwordx4 v[220:221], off
	s_waitcnt vmcnt(8)
	s_waitcnt lgkmcnt(0)
	s_barrier
	s_setprio 1
	v_mfma_f32_16x16x32_bf16 v[62:65], v[130:133], v[174:177], v[62:65]
	v_mfma_f32_16x16x32_bf16 v[58:61], v[150:153], v[174:177], v[58:61]
	v_mfma_f32_16x16x32_bf16 v[46:49], v[130:133], v[182:185], v[46:49]
	v_mfma_f32_16x16x32_bf16 v[42:45], v[150:153], v[182:185], v[42:45]
	v_mfma_f32_16x16x32_bf16 v[30:33], v[130:133], v[196:199], v[30:33]
	v_mfma_f32_16x16x32_bf16 v[26:29], v[150:153], v[196:199], v[26:29]
	v_mfma_f32_16x16x32_bf16 v[14:17], v[130:133], v[204:207], v[14:17]
	v_mfma_f32_16x16x32_bf16 v[10:13], v[150:153], v[204:207], v[10:13]
	v_mfma_f32_16x16x32_bf16 v[62:65], v[134:137], v[178:181], v[62:65]
	v_mfma_f32_16x16x32_bf16 v[58:61], v[154:157], v[178:181], v[58:61]
	v_mfma_f32_16x16x32_bf16 v[46:49], v[134:137], v[192:195], v[46:49]
	v_mfma_f32_16x16x32_bf16 v[42:45], v[154:157], v[192:195], v[42:45]
	v_mfma_f32_16x16x32_bf16 v[30:33], v[134:137], v[200:203], v[30:33]
	v_mfma_f32_16x16x32_bf16 v[26:29], v[154:157], v[200:203], v[26:29]
	v_mfma_f32_16x16x32_bf16 v[14:17], v[134:137], v[212:215], v[14:17]
	v_mfma_f32_16x16x32_bf16 v[10:13], v[154:157], v[212:215], v[10:13]
	s_setprio 0
	s_setprio 1
	v_mfma_f32_16x16x32_bf16 v[54:57], v[158:161], v[174:177], v[54:57]
	v_mfma_f32_16x16x32_bf16 v[50:53], v[166:169], v[174:177], v[50:53]
	v_mfma_f32_16x16x32_bf16 v[38:41], v[158:161], v[182:185], v[38:41]
	v_mfma_f32_16x16x32_bf16 v[34:37], v[166:169], v[182:185], v[34:37]
	v_mfma_f32_16x16x32_bf16 v[22:25], v[158:161], v[196:199], v[22:25]
	v_mfma_f32_16x16x32_bf16 v[18:21], v[166:169], v[196:199], v[18:21]
	v_mfma_f32_16x16x32_bf16 v[6:9], v[158:161], v[204:207], v[6:9]
	v_mfma_f32_16x16x32_bf16 v[2:5], v[166:169], v[204:207], v[2:5]
	v_mfma_f32_16x16x32_bf16 v[54:57], v[162:165], v[178:181], v[54:57]
	v_mfma_f32_16x16x32_bf16 v[50:53], v[170:173], v[178:181], v[50:53]
	v_mfma_f32_16x16x32_bf16 v[38:41], v[162:165], v[192:195], v[38:41]
	v_mfma_f32_16x16x32_bf16 v[34:37], v[170:173], v[192:195], v[34:37]
	v_mfma_f32_16x16x32_bf16 v[22:25], v[162:165], v[200:203], v[22:25]
	v_mfma_f32_16x16x32_bf16 v[18:21], v[170:173], v[200:203], v[18:21]
	v_mfma_f32_16x16x32_bf16 v[6:9], v[162:165], v[212:215], v[6:9]
	v_mfma_f32_16x16x32_bf16 v[2:5], v[170:173], v[212:215], v[2:5]
	s_setprio 0
	s_barrier
	s_add_i32 s6, 0, 0x18000
	s_add_i32 s14, 0, 0x1c000
	v_add_u32_e32 v154, s6, v189
	v_add_u32_e32 v170, s14, v189
	ds_read_b128 v[130:133], v154
	ds_read_b128 v[134:137], v154 offset:1024
	ds_read_b128 v[150:153], v154 offset:2048
	ds_read_b128 v[154:157], v154 offset:3072
	ds_read_b128 v[158:161], v170
	ds_read_b128 v[162:165], v170 offset:1024
	ds_read_b128 v[166:169], v170 offset:2048
	ds_read_b128 v[170:173], v170 offset:3072
	s_add_u32 s8, s12, s56
	s_addc_u32 s9, s13, s57
	s_mov_b32 m0, s39
	v_lshl_add_u64 v[222:223], s[8:9], 0, v[142:143]
	ds_read_b128 v[174:177], v190 offset:32768
	ds_read_b128 v[178:181], v190 offset:33792
	ds_read_b128 v[182:185], v190 offset:34816
	ds_read_b128 v[192:195], v190 offset:35840
	ds_read_b128 v[196:199], v190 offset:36864
	ds_read_b128 v[200:203], v190 offset:37888
	ds_read_b128 v[204:207], v190 offset:38912
	ds_read_b128 v[212:215], v190 offset:39936
	global_load_lds_dwordx4 v[222:223], off
	v_lshl_add_u64 v[222:223], s[8:9], 0, v[138:139]
	s_mov_b32 m0, s50
	s_nop 0
	global_load_lds_dwordx4 v[222:223], off
	s_waitcnt vmcnt(8)
	s_waitcnt lgkmcnt(0)
	s_barrier
	s_setprio 1
	v_mfma_f32_16x16x32_bf16 v[126:129], v[130:133], v[174:177], v[126:129]
	v_mfma_f32_16x16x32_bf16 v[122:125], v[150:153], v[174:177], v[122:125]
	v_mfma_f32_16x16x32_bf16 v[110:113], v[130:133], v[182:185], v[110:113]
	v_mfma_f32_16x16x32_bf16 v[106:109], v[150:153], v[182:185], v[106:109]
	v_mfma_f32_16x16x32_bf16 v[94:97], v[130:133], v[196:199], v[94:97]
	v_mfma_f32_16x16x32_bf16 v[90:93], v[150:153], v[196:199], v[90:93]
	v_mfma_f32_16x16x32_bf16 v[78:81], v[130:133], v[204:207], v[78:81]
	v_mfma_f32_16x16x32_bf16 v[74:77], v[150:153], v[204:207], v[74:77]
	v_mfma_f32_16x16x32_bf16 v[126:129], v[134:137], v[178:181], v[126:129]
	v_mfma_f32_16x16x32_bf16 v[122:125], v[154:157], v[178:181], v[122:125]
	v_mfma_f32_16x16x32_bf16 v[110:113], v[134:137], v[192:195], v[110:113]
	v_mfma_f32_16x16x32_bf16 v[106:109], v[154:157], v[192:195], v[106:109]
	v_mfma_f32_16x16x32_bf16 v[94:97], v[134:137], v[200:203], v[94:97]
	v_mfma_f32_16x16x32_bf16 v[90:93], v[154:157], v[200:203], v[90:93]
	v_mfma_f32_16x16x32_bf16 v[78:81], v[134:137], v[212:215], v[78:81]
	v_mfma_f32_16x16x32_bf16 v[74:77], v[154:157], v[212:215], v[74:77]
	s_setprio 0
	s_setprio 1
	v_mfma_f32_16x16x32_bf16 v[118:121], v[158:161], v[174:177], v[118:121]
	v_mfma_f32_16x16x32_bf16 v[114:117], v[166:169], v[174:177], v[114:117]
	v_mfma_f32_16x16x32_bf16 v[102:105], v[158:161], v[182:185], v[102:105]
	v_mfma_f32_16x16x32_bf16 v[98:101], v[166:169], v[182:185], v[98:101]
	v_mfma_f32_16x16x32_bf16 v[86:89], v[158:161], v[196:199], v[86:89]
	v_mfma_f32_16x16x32_bf16 v[82:85], v[166:169], v[196:199], v[82:85]
	v_mfma_f32_16x16x32_bf16 v[70:73], v[158:161], v[204:207], v[70:73]
	v_mfma_f32_16x16x32_bf16 v[66:69], v[166:169], v[204:207], v[66:69]
	v_mfma_f32_16x16x32_bf16 v[118:121], v[162:165], v[178:181], v[118:121]
	v_mfma_f32_16x16x32_bf16 v[114:117], v[170:173], v[178:181], v[114:117]
	v_mfma_f32_16x16x32_bf16 v[102:105], v[162:165], v[192:195], v[102:105]
	v_mfma_f32_16x16x32_bf16 v[98:101], v[170:173], v[192:195], v[98:101]
	v_mfma_f32_16x16x32_bf16 v[86:89], v[162:165], v[200:203], v[86:89]
	v_mfma_f32_16x16x32_bf16 v[82:85], v[170:173], v[200:203], v[82:85]
	v_mfma_f32_16x16x32_bf16 v[70:73], v[162:165], v[212:215], v[70:73]
	v_mfma_f32_16x16x32_bf16 v[66:69], v[170:173], v[212:215], v[66:69]
	s_setprio 0
	s_barrier
	s_add_i32 s6, s6, s26
	v_lshl_add_u64 v[186:187], v[186:187], 0, s[28:29]
	s_mov_b32 m0, s6
	ds_read_b128 v[174:177], v190 offset:49152
	ds_read_b128 v[178:181], v190 offset:50176
	ds_read_b128 v[182:185], v190 offset:51200
	ds_read_b128 v[192:195], v190 offset:52224
	ds_read_b128 v[196:199], v190 offset:53248
	ds_read_b128 v[200:203], v190 offset:54272
	ds_read_b128 v[204:207], v190 offset:55296
	ds_read_b128 v[212:215], v190 offset:56320
	global_load_lds_dwordx4 v[186:187], off
	v_lshl_add_u64 v[186:187], v[208:209], 0, s[28:29]
	s_add_i32 m0, s6, 0x2000
	s_add_i32 s6, s14, s26
	global_load_lds_dwordx4 v[186:187], off
	v_lshl_add_u64 v[186:187], v[210:211], 0, s[28:29]
	s_mov_b32 m0, s6
	s_nop 0
	global_load_lds_dwordx4 v[186:187], off
	v_lshl_add_u64 v[186:187], v[216:217], 0, s[28:29]
	s_add_i32 m0, s6, 0x2000
	s_nop 0
	global_load_lds_dwordx4 v[186:187], off
	v_lshl_add_u64 v[186:187], v[218:219], 0, s[28:29]
	s_mov_b32 m0, s51
	s_nop 0
	global_load_lds_dwordx4 v[186:187], off
	v_lshl_add_u64 v[186:187], v[220:221], 0, s[28:29]
	s_mov_b32 m0, s80
	s_nop 0
	global_load_lds_dwordx4 v[186:187], off
	s_waitcnt vmcnt(8)
	s_waitcnt lgkmcnt(0)
	s_barrier
	s_setprio 1
	v_mfma_f32_16x16x32_bf16 v[62:65], v[130:133], v[174:177], v[62:65]
	v_mfma_f32_16x16x32_bf16 v[58:61], v[150:153], v[174:177], v[58:61]
	v_mfma_f32_16x16x32_bf16 v[46:49], v[130:133], v[182:185], v[46:49]
	v_mfma_f32_16x16x32_bf16 v[42:45], v[150:153], v[182:185], v[42:45]
	v_mfma_f32_16x16x32_bf16 v[30:33], v[130:133], v[196:199], v[30:33]
	v_mfma_f32_16x16x32_bf16 v[26:29], v[150:153], v[196:199], v[26:29]
	v_mfma_f32_16x16x32_bf16 v[14:17], v[130:133], v[204:207], v[14:17]
	v_mfma_f32_16x16x32_bf16 v[10:13], v[150:153], v[204:207], v[10:13]
	v_mfma_f32_16x16x32_bf16 v[62:65], v[134:137], v[178:181], v[62:65]
	v_mfma_f32_16x16x32_bf16 v[58:61], v[154:157], v[178:181], v[58:61]
	v_mfma_f32_16x16x32_bf16 v[46:49], v[134:137], v[192:195], v[46:49]
	v_mfma_f32_16x16x32_bf16 v[42:45], v[154:157], v[192:195], v[42:45]
	v_mfma_f32_16x16x32_bf16 v[30:33], v[134:137], v[200:203], v[30:33]
	v_mfma_f32_16x16x32_bf16 v[26:29], v[154:157], v[200:203], v[26:29]
	v_mfma_f32_16x16x32_bf16 v[14:17], v[134:137], v[212:215], v[14:17]
	v_mfma_f32_16x16x32_bf16 v[10:13], v[154:157], v[212:215], v[10:13]
	s_setprio 0
	s_setprio 1
	v_mfma_f32_16x16x32_bf16 v[54:57], v[158:161], v[174:177], v[54:57]
	v_mfma_f32_16x16x32_bf16 v[50:53], v[166:169], v[174:177], v[50:53]
	v_mfma_f32_16x16x32_bf16 v[38:41], v[158:161], v[182:185], v[38:41]
	v_mfma_f32_16x16x32_bf16 v[34:37], v[166:169], v[182:185], v[34:37]
	v_mfma_f32_16x16x32_bf16 v[22:25], v[158:161], v[196:199], v[22:25]
	v_mfma_f32_16x16x32_bf16 v[18:21], v[166:169], v[196:199], v[18:21]
	v_mfma_f32_16x16x32_bf16 v[6:9], v[158:161], v[204:207], v[6:9]
	v_mfma_f32_16x16x32_bf16 v[2:5], v[166:169], v[204:207], v[2:5]
	v_mfma_f32_16x16x32_bf16 v[54:57], v[162:165], v[178:181], v[54:57]
	v_mfma_f32_16x16x32_bf16 v[50:53], v[170:173], v[178:181], v[50:53]
	v_mfma_f32_16x16x32_bf16 v[38:41], v[162:165], v[192:195], v[38:41]
	v_mfma_f32_16x16x32_bf16 v[34:37], v[170:173], v[192:195], v[34:37]
	v_mfma_f32_16x16x32_bf16 v[22:25], v[162:165], v[200:203], v[22:25]
	v_mfma_f32_16x16x32_bf16 v[18:21], v[170:173], v[200:203], v[18:21]
	v_mfma_f32_16x16x32_bf16 v[6:9], v[162:165], v[212:215], v[6:9]
	v_mfma_f32_16x16x32_bf16 v[2:5], v[170:173], v[212:215], v[2:5]
	s_setprio 0
	s_barrier
	s_add_u32 s1, s1, 0x100
	s_addc_u32 s5, s5, 0
	s_add_u32 s10, s10, 0x100
	s_addc_u32 s11, s11, 0
	s_cmp_ge_i32 s7, s83
	s_mov_b32 s6, s7
	s_cbranch_scc0 .LBB0_1182
